# row rmsnorm pass: gains hoisted, 4 rows per group with 16-32 row loads in flight, interleaved wave reductions (original loop kept as remainder)
# speedup vs baseline: 1.0027x; 1.0027x over previous
; DI void rms_row(const float* x, const float* gain, bf16_t* o, int lane) {
;     const f32x4* xr = (const f32x4*)x + lane; const f32x4* gr = (const f32x4*)gain + lane;
;     f32x4 v[4]; float s = 0.f;
; #pragma unroll
;     for (int j = 0; j < 4; ++j) { v[j] = xr[64 * j]; s += (v[j].x * v[j].x + v[j].y * v[j].y) + (v[j].z * v[j].z + v[j].w * v[j].w); }
;     const float rstd = rsqrtf(wave_sum(s) * (1.f / 1024.f) + 1e-6f);
; DI void phase_conv(const Args& a, int l, LAS unsigned char* lds) {
;     ...
;         for (int m = gw; m < M_TOK; m += NGW) rms_row(a.in[I_X] + (size_t)m * DM, a.in[I_MIXNORM], U + (size_t)m * DM, lane);
.LBB0_1599:
	s_or_b64 exec, exec, s[0:1]
	s_mov_b32 s0, 0x8000
	v_cmp_gt_i32_e32 vcc, s0, v0
	s_and_saveexec_b64 s[0:1], vcc
	v_readlane_b32 s20, v247, 50
	v_readlane_b32 s24, v246, 15
	v_readlane_b32 s21, v247, 51
	s_mov_b32 s22, 0x800000
	v_readlane_b32 s25, v246, 16
	s_cbranch_execz .LBB0_1602
	v_and_b32_e32 v1, 64, v190
	v_add_u32_e32 v1, 64, v1
	v_xor_b32_e32 v2, 1, v190
	v_cmp_lt_i32_e32 vcc, v2, v1
	v_readlane_b32 s4, v247, 52
	v_readlane_b32 s2, v245, 16
	v_cndmask_b32_e32 v2, v190, v2, vcc
	v_lshlrev_b32_e32 v8, 2, v2
	v_xor_b32_e32 v2, 2, v190
	v_cmp_lt_i32_e32 vcc, v2, v1
	v_lshlrev_b32_e32 v128, 4, v14
	v_readlane_b32 s5, v247, 53
	v_cndmask_b32_e32 v2, v190, v2, vcc
	v_lshlrev_b32_e32 v9, 2, v2
	v_xor_b32_e32 v2, 4, v190
	v_cmp_lt_i32_e32 vcc, v2, v1
	v_readlane_b32 s6, v247, 54
	v_readlane_b32 s7, v247, 55
	v_cndmask_b32_e32 v2, v190, v2, vcc
	v_lshlrev_b32_e32 v10, 2, v2
	v_xor_b32_e32 v2, 8, v190
	v_cmp_lt_i32_e32 vcc, v2, v1
	v_readlane_b32 s8, v247, 56
	v_readlane_b32 s9, v247, 57
	v_cndmask_b32_e32 v2, v190, v2, vcc
	v_lshlrev_b32_e32 v11, 2, v2
	v_xor_b32_e32 v2, 16, v190
	v_cmp_lt_i32_e32 vcc, v2, v1
	v_readlane_b32 s10, v247, 58
	v_readlane_b32 s11, v247, 59
	v_cndmask_b32_e32 v2, v190, v2, vcc
	v_lshlrev_b32_e32 v12, 2, v2
	v_xor_b32_e32 v2, 32, v190
	v_cmp_lt_i32_e32 vcc, v2, v1
	v_readlane_b32 s3, v245, 17
	v_lshlrev_b32_e32 v6, 3, v14
	v_cndmask_b32_e32 v1, v190, v2, vcc
	v_lshlrev_b32_e32 v13, 2, v1
	v_ashrrev_i32_e32 v1, 31, v0
	v_lshlrev_b64 v[4:5], 11, v[0:1]
	v_lshl_add_u64 v[2:3], s[6:7], 0, v[128:129]
	v_lshl_add_u64 v[4:5], s[2:3], 0, v[4:5]
	v_mov_b32_e32 v7, v129
	v_readlane_b32 s4, v249, 0
	v_lshl_add_u64 v[4:5], v[4:5], 0, v[6:7]
	v_readlane_b32 s8, v249, 4
	v_readlane_b32 s9, v249, 5
	s_mov_b64 s[2:3], 0x12600400
	v_lshlrev_b64 v[6:7], 12, v[0:1]
	v_lshl_add_u64 v[4:5], s[8:9], 0, v[4:5]
	v_lshl_add_u64 v[4:5], v[4:5], 0, s[2:3]
	v_readlane_b32 s2, v246, 4
	v_or_b32_e32 v6, v6, v128
	v_readlane_b32 s3, v246, 5
	v_readlane_b32 s12, v247, 60
	v_readlane_b32 s13, v247, 61
	v_lshl_add_u64 v[6:7], s[2:3], 0, v[6:7]
	s_mov_b64 s[2:3], 0
	v_readlane_b32 s14, v247, 62
	v_readlane_b32 s15, v247, 63
	v_readlane_b32 s16, v246, 0
	v_readlane_b32 s17, v246, 1
	v_readlane_b32 s18, v246, 2
	v_readlane_b32 s19, v246, 3
	v_readlane_b32 s5, v249, 1
	v_readlane_b32 s6, v249, 2
	v_readlane_b32 s7, v249, 3
	v_readlane_b32 s10, v249, 6
	v_readlane_b32 s11, v249, 7
	global_load_dwordx4 v[220:223], v[2:3], off
	global_load_dwordx4 v[224:227], v[2:3], off offset:1024
	global_load_dwordx4 v[228:231], v[2:3], off offset:2048
	global_load_dwordx4 v[232:235], v[2:3], off offset:3072
	global_load_dwordx4 v[64:67], v[6:7], off offset:-3072
	global_load_dwordx4 v[68:71], v[6:7], off offset:-2048
	global_load_dwordx4 v[72:75], v[6:7], off offset:-1024
	global_load_dwordx4 v[76:79], v[6:7], off
	v_lshl_add_u64 v[6:7], v[6:7], 0, s[24:25]
	global_load_dwordx4 v[80:83], v[6:7], off offset:-3072
	global_load_dwordx4 v[84:87], v[6:7], off offset:-2048
	global_load_dwordx4 v[88:91], v[6:7], off offset:-1024
	global_load_dwordx4 v[92:95], v[6:7], off
	v_lshl_add_u64 v[6:7], v[6:7], 0, s[24:25]
	global_load_dwordx4 v[96:99], v[6:7], off offset:-3072
	global_load_dwordx4 v[100:103], v[6:7], off offset:-2048
	global_load_dwordx4 v[104:107], v[6:7], off offset:-1024
	global_load_dwordx4 v[108:111], v[6:7], off
	v_lshl_add_u64 v[6:7], v[6:7], 0, s[24:25]
	global_load_dwordx4 v[112:115], v[6:7], off offset:-3072
	global_load_dwordx4 v[116:119], v[6:7], off offset:-2048
	global_load_dwordx4 v[120:123], v[6:7], off offset:-1024
	global_load_dwordx4 v[124:127], v[6:7], off
	v_lshl_add_u64 v[6:7], v[6:7], 0, s[24:25]
	global_load_dwordx4 v[130:133], v[6:7], off offset:-3072
	global_load_dwordx4 v[134:137], v[6:7], off offset:-2048
	global_load_dwordx4 v[138:141], v[6:7], off offset:-1024
	global_load_dwordx4 v[142:145], v[6:7], off
	v_lshl_add_u64 v[6:7], v[6:7], 0, s[24:25]
	global_load_dwordx4 v[146:149], v[6:7], off offset:-3072
	global_load_dwordx4 v[150:153], v[6:7], off offset:-2048
	global_load_dwordx4 v[168:171], v[6:7], off offset:-1024
	global_load_dwordx4 v[172:175], v[6:7], off
	v_lshl_add_u64 v[6:7], v[6:7], 0, s[24:25]
	global_load_dwordx4 v[176:179], v[6:7], off offset:-3072
	global_load_dwordx4 v[180:183], v[6:7], off offset:-2048
	global_load_dwordx4 v[184:187], v[6:7], off offset:-1024
	global_load_dwordx4 v[196:199], v[6:7], off
	v_lshl_add_u64 v[6:7], v[6:7], 0, s[24:25]
	global_load_dwordx4 v[200:203], v[6:7], off offset:-3072
	global_load_dwordx4 v[204:207], v[6:7], off offset:-2048
	global_load_dwordx4 v[212:215], v[6:7], off offset:-1024
	global_load_dwordx4 v[216:219], v[6:7], off
	v_lshl_add_u64 v[6:7], v[6:7], 0, s[24:25]
	s_waitcnt vmcnt(32)
	s_waitcnt vmcnt(28)
	v_pk_mul_f32 v[34:35], v[66:67], v[66:67]
	v_pk_mul_f32 v[36:37], v[64:65], v[64:65]
	v_pk_mul_f32 v[38:39], v[70:71], v[70:71]
	v_pk_mul_f32 v[40:41], v[68:69], v[68:69]
	v_pk_mov_b32 v[46:47], v[36:37], v[34:35] op_sel:[1,0]
	v_mov_b32_e32 v37, v35
	v_pk_mov_b32 v[34:35], v[40:41], v[38:39] op_sel:[1,0]
	v_mov_b32_e32 v41, v39
	v_mul_f32_e32 v45, v77, v77
	v_mul_f32_e32 v42, v73, v73
	v_mul_f32_e32 v44, v75, v75
	v_pk_add_f32 v[36:37], v[46:47], v[36:37]
	v_pk_add_f32 v[34:35], v[34:35], v[40:41]
	v_mul_f32_e32 v1, v76, v76
	v_mul_f32_e32 v48, v78, v78
	v_mul_f32_e32 v49, v79, v79
	v_pk_fma_f32 v[38:39], v[72:73], v[72:73], v[42:43] op_sel_hi:[1,1,0]
	v_pk_fma_f32 v[42:43], v[74:75], v[74:75], v[44:45] op_sel_hi:[1,1,0]
	v_pk_add_f32 v[36:37], v[36:37], v[36:37] op_sel:[0,1] op_sel_hi:[1,0]
	v_pk_add_f32 v[34:35], v[34:35], v[34:35] op_sel:[0,1] op_sel_hi:[1,0]
	v_mov_b32_e32 v39, v48
	v_mov_b32_e32 v43, v49
	v_mov_b32_e32 v37, v1
	v_mov_b32_e32 v35, v45
	v_pk_add_f32 v[38:39], v[38:39], v[42:43]
	v_pk_add_f32 v[34:35], v[36:37], v[34:35]
	s_nop 0
	v_pk_add_f32 v[34:35], v[34:35], v[38:39]
	s_nop 0
	v_add_f32_e32 v1, v34, v35
	v_mov_b32_e32 v236, v1
	s_waitcnt vmcnt(24)
; DI float wave_sum(float v) {
; #pragma unroll
;     for (int o = 1; o < 64; o <<= 1) v += __shfl_xor(v, o);
;     return v;
; DI void rms_row(const float* x, const float* gain, bf16_t* o, int lane) {
;     ...
;     for (int j = 0; j < 4; ++j) { v[j] = xr[64 * j]; s += (v[j].x * v[j].x + v[j].y * v[j].y) + (v[j].z * v[j].z + v[j].w * v[j].w); }
;     const float rstd = rsqrtf(wave_sum(s) * (1.f / 1024.f) + 1e-6f);
	v_pk_mul_f32 v[34:35], v[82:83], v[82:83]
	v_pk_mul_f32 v[36:37], v[80:81], v[80:81]
	v_pk_mul_f32 v[38:39], v[86:87], v[86:87]
	v_pk_mul_f32 v[40:41], v[84:85], v[84:85]
	v_pk_mov_b32 v[46:47], v[36:37], v[34:35] op_sel:[1,0]
	v_mov_b32_e32 v37, v35
	v_pk_mov_b32 v[34:35], v[40:41], v[38:39] op_sel:[1,0]
	v_mov_b32_e32 v41, v39
	v_mul_f32_e32 v45, v93, v93
	v_mul_f32_e32 v42, v89, v89
	v_mul_f32_e32 v44, v91, v91
	v_pk_add_f32 v[36:37], v[46:47], v[36:37]
	v_pk_add_f32 v[34:35], v[34:35], v[40:41]
	v_mul_f32_e32 v1, v92, v92
	v_mul_f32_e32 v48, v94, v94
	v_mul_f32_e32 v49, v95, v95
	v_pk_fma_f32 v[38:39], v[88:89], v[88:89], v[42:43] op_sel_hi:[1,1,0]
	v_pk_fma_f32 v[42:43], v[90:91], v[90:91], v[44:45] op_sel_hi:[1,1,0]
	v_pk_add_f32 v[36:37], v[36:37], v[36:37] op_sel:[0,1] op_sel_hi:[1,0]
	v_pk_add_f32 v[34:35], v[34:35], v[34:35] op_sel:[0,1] op_sel_hi:[1,0]
	v_mov_b32_e32 v39, v48
	v_mov_b32_e32 v43, v49
	v_mov_b32_e32 v37, v1
	v_mov_b32_e32 v35, v45
	v_pk_add_f32 v[38:39], v[38:39], v[42:43]
	v_pk_add_f32 v[34:35], v[36:37], v[34:35]
	s_nop 0
	v_pk_add_f32 v[34:35], v[34:35], v[38:39]
	s_nop 0
	v_add_f32_e32 v1, v34, v35
	v_mov_b32_e32 v237, v1
	s_waitcnt vmcnt(20)
	v_pk_mul_f32 v[34:35], v[98:99], v[98:99]
	v_pk_mul_f32 v[36:37], v[96:97], v[96:97]
	v_pk_mul_f32 v[38:39], v[102:103], v[102:103]
	v_pk_mul_f32 v[40:41], v[100:101], v[100:101]
	v_pk_mov_b32 v[46:47], v[36:37], v[34:35] op_sel:[1,0]
	v_mov_b32_e32 v37, v35
	v_pk_mov_b32 v[34:35], v[40:41], v[38:39] op_sel:[1,0]
	v_mov_b32_e32 v41, v39
	v_mul_f32_e32 v45, v109, v109
	v_mul_f32_e32 v42, v105, v105
	v_mul_f32_e32 v44, v107, v107
	v_pk_add_f32 v[36:37], v[46:47], v[36:37]
	v_pk_add_f32 v[34:35], v[34:35], v[40:41]
	v_mul_f32_e32 v1, v108, v108
	v_mul_f32_e32 v48, v110, v110
	v_mul_f32_e32 v49, v111, v111
	v_pk_fma_f32 v[38:39], v[104:105], v[104:105], v[42:43] op_sel_hi:[1,1,0]
	v_pk_fma_f32 v[42:43], v[106:107], v[106:107], v[44:45] op_sel_hi:[1,1,0]
	v_pk_add_f32 v[36:37], v[36:37], v[36:37] op_sel:[0,1] op_sel_hi:[1,0]
	v_pk_add_f32 v[34:35], v[34:35], v[34:35] op_sel:[0,1] op_sel_hi:[1,0]
	v_mov_b32_e32 v39, v48
	v_mov_b32_e32 v43, v49
	v_mov_b32_e32 v37, v1
	v_mov_b32_e32 v35, v45
	v_pk_add_f32 v[38:39], v[38:39], v[42:43]
	v_pk_add_f32 v[34:35], v[36:37], v[34:35]
	s_nop 0
	v_pk_add_f32 v[34:35], v[34:35], v[38:39]
	s_nop 0
	v_add_f32_e32 v1, v34, v35
	v_mov_b32_e32 v238, v1
	s_waitcnt vmcnt(16)
	v_pk_mul_f32 v[34:35], v[114:115], v[114:115]
	v_pk_mul_f32 v[36:37], v[112:113], v[112:113]
	v_pk_mul_f32 v[38:39], v[118:119], v[118:119]
	v_pk_mul_f32 v[40:41], v[116:117], v[116:117]
	v_pk_mov_b32 v[46:47], v[36:37], v[34:35] op_sel:[1,0]
	v_mov_b32_e32 v37, v35
	v_pk_mov_b32 v[34:35], v[40:41], v[38:39] op_sel:[1,0]
	v_mov_b32_e32 v41, v39
	v_mul_f32_e32 v45, v125, v125
	v_mul_f32_e32 v42, v121, v121
	v_mul_f32_e32 v44, v123, v123
	v_pk_add_f32 v[36:37], v[46:47], v[36:37]
	v_pk_add_f32 v[34:35], v[34:35], v[40:41]
	v_mul_f32_e32 v1, v124, v124
	v_mul_f32_e32 v48, v126, v126
	v_mul_f32_e32 v49, v127, v127
	v_pk_fma_f32 v[38:39], v[120:121], v[120:121], v[42:43] op_sel_hi:[1,1,0]
	v_pk_fma_f32 v[42:43], v[122:123], v[122:123], v[44:45] op_sel_hi:[1,1,0]
	v_pk_add_f32 v[36:37], v[36:37], v[36:37] op_sel:[0,1] op_sel_hi:[1,0]
	v_pk_add_f32 v[34:35], v[34:35], v[34:35] op_sel:[0,1] op_sel_hi:[1,0]
	v_mov_b32_e32 v39, v48
	v_mov_b32_e32 v43, v49
	v_mov_b32_e32 v37, v1
	v_mov_b32_e32 v35, v45
	v_pk_add_f32 v[38:39], v[38:39], v[42:43]
	v_pk_add_f32 v[34:35], v[36:37], v[34:35]
	s_nop 0
	v_pk_add_f32 v[34:35], v[34:35], v[38:39]
	s_nop 0
	v_add_f32_e32 v1, v34, v35
	v_mov_b32_e32 v239, v1
	ds_bpermute_b32 v240, v8, v236
	ds_bpermute_b32 v241, v8, v237
	ds_bpermute_b32 v242, v8, v238
	ds_bpermute_b32 v243, v8, v239
	s_waitcnt lgkmcnt(3)
	v_add_f32_e32 v236, v236, v240
	s_waitcnt lgkmcnt(2)
	v_add_f32_e32 v237, v237, v241
	s_waitcnt lgkmcnt(1)
	v_add_f32_e32 v238, v238, v242
	s_waitcnt lgkmcnt(0)
	v_add_f32_e32 v239, v239, v243
	ds_bpermute_b32 v240, v9, v236
	ds_bpermute_b32 v241, v9, v237
	ds_bpermute_b32 v242, v9, v238
	ds_bpermute_b32 v243, v9, v239
	s_waitcnt lgkmcnt(3)
	v_add_f32_e32 v236, v236, v240
	s_waitcnt lgkmcnt(2)
	v_add_f32_e32 v237, v237, v241
	s_waitcnt lgkmcnt(1)
	v_add_f32_e32 v238, v238, v242
	s_waitcnt lgkmcnt(0)
	v_add_f32_e32 v239, v239, v243
	ds_bpermute_b32 v240, v10, v236
	ds_bpermute_b32 v241, v10, v237
	ds_bpermute_b32 v242, v10, v238
	ds_bpermute_b32 v243, v10, v239
	s_waitcnt lgkmcnt(3)
	v_add_f32_e32 v236, v236, v240
	s_waitcnt lgkmcnt(2)
	v_add_f32_e32 v237, v237, v241
	s_waitcnt lgkmcnt(1)
	v_add_f32_e32 v238, v238, v242
	s_waitcnt lgkmcnt(0)
	v_add_f32_e32 v239, v239, v243
	ds_bpermute_b32 v240, v11, v236
	ds_bpermute_b32 v241, v11, v237
	ds_bpermute_b32 v242, v11, v238
	ds_bpermute_b32 v243, v11, v239
	s_waitcnt lgkmcnt(3)
	v_add_f32_e32 v236, v236, v240
	s_waitcnt lgkmcnt(2)
	v_add_f32_e32 v237, v237, v241
	s_waitcnt lgkmcnt(1)
	v_add_f32_e32 v238, v238, v242
	s_waitcnt lgkmcnt(0)
	v_add_f32_e32 v239, v239, v243
	ds_bpermute_b32 v240, v12, v236
	ds_bpermute_b32 v241, v12, v237
	ds_bpermute_b32 v242, v12, v238
	ds_bpermute_b32 v243, v12, v239
	s_waitcnt lgkmcnt(3)
	v_add_f32_e32 v236, v236, v240
	s_waitcnt lgkmcnt(2)
	v_add_f32_e32 v237, v237, v241
	s_waitcnt lgkmcnt(1)
	v_add_f32_e32 v238, v238, v242
	s_waitcnt lgkmcnt(0)
	v_add_f32_e32 v239, v239, v243
	ds_bpermute_b32 v240, v13, v236
	ds_bpermute_b32 v241, v13, v237
	ds_bpermute_b32 v242, v13, v238
	ds_bpermute_b32 v243, v13, v239
	s_waitcnt lgkmcnt(3)
	v_add_f32_e32 v236, v236, v240
	s_waitcnt lgkmcnt(2)
	v_add_f32_e32 v237, v237, v241
	s_waitcnt lgkmcnt(1)
; DI unsigned pk2(float a, float b) { f32x2 v = {a, b}; bf2_t r = __builtin_convertvector(v, bf2_t); return __builtin_bit_cast(unsigned, r); }
; DI void rms_row(const float* x, const float* gain, bf16_t* o, int lane) {
;     ...
;     const float rstd = rsqrtf(wave_sum(s) * (1.f / 1024.f) + 1e-6f);
;     u32x2* op = (u32x2*)o + lane;
; #pragma unroll
;     for (int j = 0; j < 4; ++j) { const f32x4 g = gr[64 * j]; u32x2 w; w.x = pk2(v[j].x * rstd * g.x, v[j].y * rstd * g.y); w.y = pk2(v[j].z * rstd * g.z, v[j].w * rstd * g.w); op[64 * j] = w; }
	v_add_f32_e32 v238, v238, v242
	s_waitcnt lgkmcnt(0)
	v_add_f32_e32 v239, v239, v243
	v_mov_b32_e32 v1, v236
	v_fmamk_f32 v1, v1, 0x3a800000, v154
	v_mul_f32_e32 v34, 0x4b800000, v1
	v_cmp_gt_f32_e32 vcc, s22, v1
	s_nop 1
	v_cndmask_b32_e32 v1, v1, v34, vcc
	v_rsq_f32_e32 v1, v1
	s_nop 0
	v_mul_f32_e32 v34, 0x45800000, v1
	v_cndmask_b32_e32 v34, v1, v34, vcc
	v_pk_mul_f32 v[64:65], v[64:65], v[34:35] op_sel_hi:[1,0]
	v_pk_mul_f32 v[66:67], v[66:67], v[34:35] op_sel_hi:[1,0]
	v_pk_mul_f32 v[64:65], v[220:221], v[64:65]
	v_pk_mul_f32 v[66:67], v[222:223], v[66:67]
	v_cvt_pk_bf16_f32 v64, v64, v65
	v_cvt_pk_bf16_f32 v65, v66, v67
	v_pk_mul_f32 v[68:69], v[68:69], v[34:35] op_sel_hi:[1,0]
	v_pk_mul_f32 v[70:71], v[70:71], v[34:35] op_sel_hi:[1,0]
	v_pk_mul_f32 v[68:69], v[224:225], v[68:69]
	v_pk_mul_f32 v[70:71], v[226:227], v[70:71]
	v_cvt_pk_bf16_f32 v68, v68, v69
	v_cvt_pk_bf16_f32 v69, v70, v71
	v_pk_mul_f32 v[72:73], v[72:73], v[34:35] op_sel_hi:[1,0]
	v_pk_mul_f32 v[74:75], v[74:75], v[34:35] op_sel_hi:[1,0]
	v_pk_mul_f32 v[72:73], v[228:229], v[72:73]
	v_pk_mul_f32 v[74:75], v[230:231], v[74:75]
	v_cvt_pk_bf16_f32 v72, v72, v73
	v_cvt_pk_bf16_f32 v73, v74, v75
	v_pk_mul_f32 v[76:77], v[76:77], v[34:35] op_sel_hi:[1,0]
	v_pk_mul_f32 v[78:79], v[78:79], v[34:35] op_sel_hi:[1,0]
	v_pk_mul_f32 v[76:77], v[232:233], v[76:77]
	v_pk_mul_f32 v[78:79], v[234:235], v[78:79]
	v_cvt_pk_bf16_f32 v76, v76, v77
	v_cvt_pk_bf16_f32 v77, v78, v79
	global_store_dwordx2 v[4:5], v[64:65], off offset:-1024
	global_store_dwordx2 v[4:5], v[68:69], off offset:-512
	global_store_dwordx2 v[4:5], v[72:73], off
	global_store_dwordx2 v[4:5], v[76:77], off offset:512
	v_lshl_add_u64 v[4:5], v[4:5], 0, s[20:21]
	v_add_u32_e32 v0, s76, v0
	v_mov_b32_e32 v1, v237
	v_fmamk_f32 v1, v1, 0x3a800000, v154
	v_mul_f32_e32 v34, 0x4b800000, v1
	v_cmp_gt_f32_e32 vcc, s22, v1
	s_nop 1
	v_cndmask_b32_e32 v1, v1, v34, vcc
	v_rsq_f32_e32 v1, v1
	s_nop 0
	v_mul_f32_e32 v34, 0x45800000, v1
	v_cndmask_b32_e32 v34, v1, v34, vcc
	v_pk_mul_f32 v[80:81], v[80:81], v[34:35] op_sel_hi:[1,0]
	v_pk_mul_f32 v[82:83], v[82:83], v[34:35] op_sel_hi:[1,0]
	v_pk_mul_f32 v[80:81], v[220:221], v[80:81]
	v_pk_mul_f32 v[82:83], v[222:223], v[82:83]
	v_cvt_pk_bf16_f32 v80, v80, v81
	v_cvt_pk_bf16_f32 v81, v82, v83
	v_pk_mul_f32 v[84:85], v[84:85], v[34:35] op_sel_hi:[1,0]
	v_pk_mul_f32 v[86:87], v[86:87], v[34:35] op_sel_hi:[1,0]
	v_pk_mul_f32 v[84:85], v[224:225], v[84:85]
	v_pk_mul_f32 v[86:87], v[226:227], v[86:87]
	v_cvt_pk_bf16_f32 v84, v84, v85
	v_cvt_pk_bf16_f32 v85, v86, v87
	v_pk_mul_f32 v[88:89], v[88:89], v[34:35] op_sel_hi:[1,0]
	v_pk_mul_f32 v[90:91], v[90:91], v[34:35] op_sel_hi:[1,0]
	v_pk_mul_f32 v[88:89], v[228:229], v[88:89]
	v_pk_mul_f32 v[90:91], v[230:231], v[90:91]
	v_cvt_pk_bf16_f32 v88, v88, v89
	v_cvt_pk_bf16_f32 v89, v90, v91
	v_pk_mul_f32 v[92:93], v[92:93], v[34:35] op_sel_hi:[1,0]
	v_pk_mul_f32 v[94:95], v[94:95], v[34:35] op_sel_hi:[1,0]
	v_pk_mul_f32 v[92:93], v[232:233], v[92:93]
	v_pk_mul_f32 v[94:95], v[234:235], v[94:95]
	v_cvt_pk_bf16_f32 v92, v92, v93
	v_cvt_pk_bf16_f32 v93, v94, v95
	global_store_dwordx2 v[4:5], v[80:81], off offset:-1024
	global_store_dwordx2 v[4:5], v[84:85], off offset:-512
	global_store_dwordx2 v[4:5], v[88:89], off
	global_store_dwordx2 v[4:5], v[92:93], off offset:512
	v_lshl_add_u64 v[4:5], v[4:5], 0, s[20:21]
	v_add_u32_e32 v0, s76, v0
	v_mov_b32_e32 v1, v238
	v_fmamk_f32 v1, v1, 0x3a800000, v154
	v_mul_f32_e32 v34, 0x4b800000, v1
	v_cmp_gt_f32_e32 vcc, s22, v1
	s_nop 1
	v_cndmask_b32_e32 v1, v1, v34, vcc
	v_rsq_f32_e32 v1, v1
	s_nop 0
	v_mul_f32_e32 v34, 0x45800000, v1
	v_cndmask_b32_e32 v34, v1, v34, vcc
	v_pk_mul_f32 v[96:97], v[96:97], v[34:35] op_sel_hi:[1,0]
	v_pk_mul_f32 v[98:99], v[98:99], v[34:35] op_sel_hi:[1,0]
	v_pk_mul_f32 v[96:97], v[220:221], v[96:97]
	v_pk_mul_f32 v[98:99], v[222:223], v[98:99]
	v_cvt_pk_bf16_f32 v96, v96, v97
	v_cvt_pk_bf16_f32 v97, v98, v99
	v_pk_mul_f32 v[100:101], v[100:101], v[34:35] op_sel_hi:[1,0]
	v_pk_mul_f32 v[102:103], v[102:103], v[34:35] op_sel_hi:[1,0]
	v_pk_mul_f32 v[100:101], v[224:225], v[100:101]
	v_pk_mul_f32 v[102:103], v[226:227], v[102:103]
	v_cvt_pk_bf16_f32 v100, v100, v101
	v_cvt_pk_bf16_f32 v101, v102, v103
	v_pk_mul_f32 v[104:105], v[104:105], v[34:35] op_sel_hi:[1,0]
	v_pk_mul_f32 v[106:107], v[106:107], v[34:35] op_sel_hi:[1,0]
	v_pk_mul_f32 v[104:105], v[228:229], v[104:105]
	v_pk_mul_f32 v[106:107], v[230:231], v[106:107]
	v_cvt_pk_bf16_f32 v104, v104, v105
	v_cvt_pk_bf16_f32 v105, v106, v107
	v_pk_mul_f32 v[108:109], v[108:109], v[34:35] op_sel_hi:[1,0]
	v_pk_mul_f32 v[110:111], v[110:111], v[34:35] op_sel_hi:[1,0]
	v_pk_mul_f32 v[108:109], v[232:233], v[108:109]
	v_pk_mul_f32 v[110:111], v[234:235], v[110:111]
	v_cvt_pk_bf16_f32 v108, v108, v109
	v_cvt_pk_bf16_f32 v109, v110, v111
	global_store_dwordx2 v[4:5], v[96:97], off offset:-1024
	global_store_dwordx2 v[4:5], v[100:101], off offset:-512
	global_store_dwordx2 v[4:5], v[104:105], off
	global_store_dwordx2 v[4:5], v[108:109], off offset:512
	v_lshl_add_u64 v[4:5], v[4:5], 0, s[20:21]
	v_add_u32_e32 v0, s76, v0
	v_mov_b32_e32 v1, v239
	v_fmamk_f32 v1, v1, 0x3a800000, v154
	v_mul_f32_e32 v34, 0x4b800000, v1
	v_cmp_gt_f32_e32 vcc, s22, v1
	s_nop 1
	v_cndmask_b32_e32 v1, v1, v34, vcc
	v_rsq_f32_e32 v1, v1
	s_nop 0
	v_mul_f32_e32 v34, 0x45800000, v1
	v_cndmask_b32_e32 v34, v1, v34, vcc
	v_pk_mul_f32 v[112:113], v[112:113], v[34:35] op_sel_hi:[1,0]
	v_pk_mul_f32 v[114:115], v[114:115], v[34:35] op_sel_hi:[1,0]
	v_pk_mul_f32 v[112:113], v[220:221], v[112:113]
	v_pk_mul_f32 v[114:115], v[222:223], v[114:115]
; DI unsigned pk2(float a, float b) { f32x2 v = {a, b}; bf2_t r = __builtin_convertvector(v, bf2_t); return __builtin_bit_cast(unsigned, r); }
; DI void rms_row(const float* x, const float* gain, bf16_t* o, int lane) {
;     const f32x4* xr = (const f32x4*)x + lane; const f32x4* gr = (const f32x4*)gain + lane;
;     f32x4 v[4]; float s = 0.f;
; #pragma unroll
;     for (int j = 0; j < 4; ++j) { v[j] = xr[64 * j]; s += (v[j].x * v[j].x + v[j].y * v[j].y) + (v[j].z * v[j].z + v[j].w * v[j].w); }
;     const float rstd = rsqrtf(wave_sum(s) * (1.f / 1024.f) + 1e-6f);
;     u32x2* op = (u32x2*)o + lane;
; #pragma unroll
;     for (int j = 0; j < 4; ++j) { const f32x4 g = gr[64 * j]; u32x2 w; w.x = pk2(v[j].x * rstd * g.x, v[j].y * rstd * g.y); w.y = pk2(v[j].z * rstd * g.z, v[j].w * rstd * g.w); op[64 * j] = w; }
	v_cvt_pk_bf16_f32 v112, v112, v113
	v_cvt_pk_bf16_f32 v113, v114, v115
	v_pk_mul_f32 v[116:117], v[116:117], v[34:35] op_sel_hi:[1,0]
	v_pk_mul_f32 v[118:119], v[118:119], v[34:35] op_sel_hi:[1,0]
	v_pk_mul_f32 v[116:117], v[224:225], v[116:117]
	v_pk_mul_f32 v[118:119], v[226:227], v[118:119]
	v_cvt_pk_bf16_f32 v116, v116, v117
	v_cvt_pk_bf16_f32 v117, v118, v119
	v_pk_mul_f32 v[120:121], v[120:121], v[34:35] op_sel_hi:[1,0]
	v_pk_mul_f32 v[122:123], v[122:123], v[34:35] op_sel_hi:[1,0]
	v_pk_mul_f32 v[120:121], v[228:229], v[120:121]
	v_pk_mul_f32 v[122:123], v[230:231], v[122:123]
	v_cvt_pk_bf16_f32 v120, v120, v121
	v_cvt_pk_bf16_f32 v121, v122, v123
	v_pk_mul_f32 v[124:125], v[124:125], v[34:35] op_sel_hi:[1,0]
	v_pk_mul_f32 v[126:127], v[126:127], v[34:35] op_sel_hi:[1,0]
	v_pk_mul_f32 v[124:125], v[232:233], v[124:125]
	v_pk_mul_f32 v[126:127], v[234:235], v[126:127]
	v_cvt_pk_bf16_f32 v124, v124, v125
	v_cvt_pk_bf16_f32 v125, v126, v127
	global_store_dwordx2 v[4:5], v[112:113], off offset:-1024
	global_store_dwordx2 v[4:5], v[116:117], off offset:-512
	global_store_dwordx2 v[4:5], v[120:121], off
	global_store_dwordx2 v[4:5], v[124:125], off offset:512
	v_lshl_add_u64 v[4:5], v[4:5], 0, s[20:21]
	v_add_u32_e32 v0, s76, v0
	global_load_dwordx4 v[64:67], v[6:7], off offset:-3072
	global_load_dwordx4 v[68:71], v[6:7], off offset:-2048
	global_load_dwordx4 v[72:75], v[6:7], off offset:-1024
	global_load_dwordx4 v[76:79], v[6:7], off
	v_lshl_add_u64 v[6:7], v[6:7], 0, s[24:25]
	global_load_dwordx4 v[80:83], v[6:7], off offset:-3072
	global_load_dwordx4 v[84:87], v[6:7], off offset:-2048
	global_load_dwordx4 v[88:91], v[6:7], off offset:-1024
	global_load_dwordx4 v[92:95], v[6:7], off
	v_lshl_add_u64 v[6:7], v[6:7], 0, s[24:25]
	global_load_dwordx4 v[96:99], v[6:7], off offset:-3072
	global_load_dwordx4 v[100:103], v[6:7], off offset:-2048
	global_load_dwordx4 v[104:107], v[6:7], off offset:-1024
	global_load_dwordx4 v[108:111], v[6:7], off
	v_lshl_add_u64 v[6:7], v[6:7], 0, s[24:25]
	global_load_dwordx4 v[112:115], v[6:7], off offset:-3072
	global_load_dwordx4 v[116:119], v[6:7], off offset:-2048
	global_load_dwordx4 v[120:123], v[6:7], off offset:-1024
	global_load_dwordx4 v[124:127], v[6:7], off
	v_lshl_add_u64 v[6:7], v[6:7], 0, s[24:25]
	s_waitcnt vmcnt(28)
	v_pk_mul_f32 v[34:35], v[132:133], v[132:133]
	v_pk_mul_f32 v[36:37], v[130:131], v[130:131]
	v_pk_mul_f32 v[38:39], v[136:137], v[136:137]
	v_pk_mul_f32 v[40:41], v[134:135], v[134:135]
	v_pk_mov_b32 v[46:47], v[36:37], v[34:35] op_sel:[1,0]
	v_mov_b32_e32 v37, v35
	v_pk_mov_b32 v[34:35], v[40:41], v[38:39] op_sel:[1,0]
	v_mov_b32_e32 v41, v39
	v_mul_f32_e32 v45, v143, v143
	v_mul_f32_e32 v42, v139, v139
	v_mul_f32_e32 v44, v141, v141
	v_pk_add_f32 v[36:37], v[46:47], v[36:37]
	v_pk_add_f32 v[34:35], v[34:35], v[40:41]
	v_mul_f32_e32 v1, v142, v142
	v_mul_f32_e32 v48, v144, v144
	v_mul_f32_e32 v49, v145, v145
	v_pk_fma_f32 v[38:39], v[138:139], v[138:139], v[42:43] op_sel_hi:[1,1,0]
	v_pk_fma_f32 v[42:43], v[140:141], v[140:141], v[44:45] op_sel_hi:[1,1,0]
	v_pk_add_f32 v[36:37], v[36:37], v[36:37] op_sel:[0,1] op_sel_hi:[1,0]
	v_pk_add_f32 v[34:35], v[34:35], v[34:35] op_sel:[0,1] op_sel_hi:[1,0]
	v_mov_b32_e32 v39, v48
	v_mov_b32_e32 v43, v49
	v_mov_b32_e32 v37, v1
	v_mov_b32_e32 v35, v45
	v_pk_add_f32 v[38:39], v[38:39], v[42:43]
	v_pk_add_f32 v[34:35], v[36:37], v[34:35]
	s_nop 0
	v_pk_add_f32 v[34:35], v[34:35], v[38:39]
	s_nop 0
	v_add_f32_e32 v1, v34, v35
	v_mov_b32_e32 v236, v1
	s_waitcnt vmcnt(24)
	v_pk_mul_f32 v[34:35], v[148:149], v[148:149]
	v_pk_mul_f32 v[36:37], v[146:147], v[146:147]
	v_pk_mul_f32 v[38:39], v[152:153], v[152:153]
	v_pk_mul_f32 v[40:41], v[150:151], v[150:151]
	v_pk_mov_b32 v[46:47], v[36:37], v[34:35] op_sel:[1,0]
	v_mov_b32_e32 v37, v35
	v_pk_mov_b32 v[34:35], v[40:41], v[38:39] op_sel:[1,0]
	v_mov_b32_e32 v41, v39
	v_mul_f32_e32 v45, v173, v173
	v_mul_f32_e32 v42, v169, v169
	v_mul_f32_e32 v44, v171, v171
	v_pk_add_f32 v[36:37], v[46:47], v[36:37]
	v_pk_add_f32 v[34:35], v[34:35], v[40:41]
	v_mul_f32_e32 v1, v172, v172
	v_mul_f32_e32 v48, v174, v174
	v_mul_f32_e32 v49, v175, v175
	v_pk_fma_f32 v[38:39], v[168:169], v[168:169], v[42:43] op_sel_hi:[1,1,0]
	v_pk_fma_f32 v[42:43], v[170:171], v[170:171], v[44:45] op_sel_hi:[1,1,0]
	v_pk_add_f32 v[36:37], v[36:37], v[36:37] op_sel:[0,1] op_sel_hi:[1,0]
	v_pk_add_f32 v[34:35], v[34:35], v[34:35] op_sel:[0,1] op_sel_hi:[1,0]
	v_mov_b32_e32 v39, v48
	v_mov_b32_e32 v43, v49
	v_mov_b32_e32 v37, v1
	v_mov_b32_e32 v35, v45
	v_pk_add_f32 v[38:39], v[38:39], v[42:43]
	v_pk_add_f32 v[34:35], v[36:37], v[34:35]
	s_nop 0
	v_pk_add_f32 v[34:35], v[34:35], v[38:39]
	s_nop 0
	v_add_f32_e32 v1, v34, v35
	v_mov_b32_e32 v237, v1
	s_waitcnt vmcnt(20)
	v_pk_mul_f32 v[34:35], v[178:179], v[178:179]
	v_pk_mul_f32 v[36:37], v[176:177], v[176:177]
	v_pk_mul_f32 v[38:39], v[182:183], v[182:183]
	v_pk_mul_f32 v[40:41], v[180:181], v[180:181]
	v_pk_mov_b32 v[46:47], v[36:37], v[34:35] op_sel:[1,0]
	v_mov_b32_e32 v37, v35
	v_pk_mov_b32 v[34:35], v[40:41], v[38:39] op_sel:[1,0]
	v_mov_b32_e32 v41, v39
	v_mul_f32_e32 v45, v197, v197
	v_mul_f32_e32 v42, v185, v185
	v_mul_f32_e32 v44, v187, v187
	v_pk_add_f32 v[36:37], v[46:47], v[36:37]
	v_pk_add_f32 v[34:35], v[34:35], v[40:41]
	v_mul_f32_e32 v1, v196, v196
	v_mul_f32_e32 v48, v198, v198
	v_mul_f32_e32 v49, v199, v199
	v_pk_fma_f32 v[38:39], v[184:185], v[184:185], v[42:43] op_sel_hi:[1,1,0]
	v_pk_fma_f32 v[42:43], v[186:187], v[186:187], v[44:45] op_sel_hi:[1,1,0]
	v_pk_add_f32 v[36:37], v[36:37], v[36:37] op_sel:[0,1] op_sel_hi:[1,0]
	v_pk_add_f32 v[34:35], v[34:35], v[34:35] op_sel:[0,1] op_sel_hi:[1,0]
	v_mov_b32_e32 v39, v48
	v_mov_b32_e32 v43, v49
	v_mov_b32_e32 v37, v1
	v_mov_b32_e32 v35, v45
	v_pk_add_f32 v[38:39], v[38:39], v[42:43]
	v_pk_add_f32 v[34:35], v[36:37], v[34:35]
	s_nop 0
	v_pk_add_f32 v[34:35], v[34:35], v[38:39]
	s_nop 0
	v_add_f32_e32 v1, v34, v35
	v_mov_b32_e32 v238, v1
	s_waitcnt vmcnt(16)
; DI unsigned pk2(float a, float b) { f32x2 v = {a, b}; bf2_t r = __builtin_convertvector(v, bf2_t); return __builtin_bit_cast(unsigned, r); }
; DI float wave_sum(float v) {
; #pragma unroll
;     for (int o = 1; o < 64; o <<= 1) v += __shfl_xor(v, o);
;     return v;
; DI void rms_row(const float* x, const float* gain, bf16_t* o, int lane) {
;     ...
;     for (int j = 0; j < 4; ++j) { v[j] = xr[64 * j]; s += (v[j].x * v[j].x + v[j].y * v[j].y) + (v[j].z * v[j].z + v[j].w * v[j].w); }
;     const float rstd = rsqrtf(wave_sum(s) * (1.f / 1024.f) + 1e-6f);
;     u32x2* op = (u32x2*)o + lane;
; #pragma unroll
;     for (int j = 0; j < 4; ++j) { const f32x4 g = gr[64 * j]; u32x2 w; w.x = pk2(v[j].x * rstd * g.x, v[j].y * rstd * g.y); w.y = pk2(v[j].z * rstd * g.z, v[j].w * rstd * g.w); op[64 * j] = w; }
	v_pk_mul_f32 v[34:35], v[202:203], v[202:203]
	v_pk_mul_f32 v[36:37], v[200:201], v[200:201]
	v_pk_mul_f32 v[38:39], v[206:207], v[206:207]
	v_pk_mul_f32 v[40:41], v[204:205], v[204:205]
	v_pk_mov_b32 v[46:47], v[36:37], v[34:35] op_sel:[1,0]
	v_mov_b32_e32 v37, v35
	v_pk_mov_b32 v[34:35], v[40:41], v[38:39] op_sel:[1,0]
	v_mov_b32_e32 v41, v39
	v_mul_f32_e32 v45, v217, v217
	v_mul_f32_e32 v42, v213, v213
	v_mul_f32_e32 v44, v215, v215
	v_pk_add_f32 v[36:37], v[46:47], v[36:37]
	v_pk_add_f32 v[34:35], v[34:35], v[40:41]
	v_mul_f32_e32 v1, v216, v216
	v_mul_f32_e32 v48, v218, v218
	v_mul_f32_e32 v49, v219, v219
	v_pk_fma_f32 v[38:39], v[212:213], v[212:213], v[42:43] op_sel_hi:[1,1,0]
	v_pk_fma_f32 v[42:43], v[214:215], v[214:215], v[44:45] op_sel_hi:[1,1,0]
	v_pk_add_f32 v[36:37], v[36:37], v[36:37] op_sel:[0,1] op_sel_hi:[1,0]
	v_pk_add_f32 v[34:35], v[34:35], v[34:35] op_sel:[0,1] op_sel_hi:[1,0]
	v_mov_b32_e32 v39, v48
	v_mov_b32_e32 v43, v49
	v_mov_b32_e32 v37, v1
	v_mov_b32_e32 v35, v45
	v_pk_add_f32 v[38:39], v[38:39], v[42:43]
	v_pk_add_f32 v[34:35], v[36:37], v[34:35]
	s_nop 0
	v_pk_add_f32 v[34:35], v[34:35], v[38:39]
	s_nop 0
	v_add_f32_e32 v1, v34, v35
	v_mov_b32_e32 v239, v1
	ds_bpermute_b32 v240, v8, v236
	ds_bpermute_b32 v241, v8, v237
	ds_bpermute_b32 v242, v8, v238
	ds_bpermute_b32 v243, v8, v239
	s_waitcnt lgkmcnt(3)
	v_add_f32_e32 v236, v236, v240
	s_waitcnt lgkmcnt(2)
	v_add_f32_e32 v237, v237, v241
	s_waitcnt lgkmcnt(1)
	v_add_f32_e32 v238, v238, v242
	s_waitcnt lgkmcnt(0)
	v_add_f32_e32 v239, v239, v243
	ds_bpermute_b32 v240, v9, v236
	ds_bpermute_b32 v241, v9, v237
	ds_bpermute_b32 v242, v9, v238
	ds_bpermute_b32 v243, v9, v239
	s_waitcnt lgkmcnt(3)
	v_add_f32_e32 v236, v236, v240
	s_waitcnt lgkmcnt(2)
	v_add_f32_e32 v237, v237, v241
	s_waitcnt lgkmcnt(1)
	v_add_f32_e32 v238, v238, v242
	s_waitcnt lgkmcnt(0)
	v_add_f32_e32 v239, v239, v243
	ds_bpermute_b32 v240, v10, v236
	ds_bpermute_b32 v241, v10, v237
	ds_bpermute_b32 v242, v10, v238
	ds_bpermute_b32 v243, v10, v239
	s_waitcnt lgkmcnt(3)
	v_add_f32_e32 v236, v236, v240
	s_waitcnt lgkmcnt(2)
	v_add_f32_e32 v237, v237, v241
	s_waitcnt lgkmcnt(1)
	v_add_f32_e32 v238, v238, v242
	s_waitcnt lgkmcnt(0)
	v_add_f32_e32 v239, v239, v243
	ds_bpermute_b32 v240, v11, v236
	ds_bpermute_b32 v241, v11, v237
	ds_bpermute_b32 v242, v11, v238
	ds_bpermute_b32 v243, v11, v239
	s_waitcnt lgkmcnt(3)
	v_add_f32_e32 v236, v236, v240
	s_waitcnt lgkmcnt(2)
	v_add_f32_e32 v237, v237, v241
	s_waitcnt lgkmcnt(1)
	v_add_f32_e32 v238, v238, v242
	s_waitcnt lgkmcnt(0)
	v_add_f32_e32 v239, v239, v243
	ds_bpermute_b32 v240, v12, v236
	ds_bpermute_b32 v241, v12, v237
	ds_bpermute_b32 v242, v12, v238
	ds_bpermute_b32 v243, v12, v239
	s_waitcnt lgkmcnt(3)
	v_add_f32_e32 v236, v236, v240
	s_waitcnt lgkmcnt(2)
	v_add_f32_e32 v237, v237, v241
	s_waitcnt lgkmcnt(1)
	v_add_f32_e32 v238, v238, v242
	s_waitcnt lgkmcnt(0)
	v_add_f32_e32 v239, v239, v243
	ds_bpermute_b32 v240, v13, v236
	ds_bpermute_b32 v241, v13, v237
	ds_bpermute_b32 v242, v13, v238
	ds_bpermute_b32 v243, v13, v239
	s_waitcnt lgkmcnt(3)
	v_add_f32_e32 v236, v236, v240
	s_waitcnt lgkmcnt(2)
	v_add_f32_e32 v237, v237, v241
	s_waitcnt lgkmcnt(1)
	v_add_f32_e32 v238, v238, v242
	s_waitcnt lgkmcnt(0)
	v_add_f32_e32 v239, v239, v243
	v_mov_b32_e32 v1, v236
	v_fmamk_f32 v1, v1, 0x3a800000, v154
	v_mul_f32_e32 v34, 0x4b800000, v1
	v_cmp_gt_f32_e32 vcc, s22, v1
	s_nop 1
	v_cndmask_b32_e32 v1, v1, v34, vcc
	v_rsq_f32_e32 v1, v1
	s_nop 0
	v_mul_f32_e32 v34, 0x45800000, v1
	v_cndmask_b32_e32 v34, v1, v34, vcc
	v_pk_mul_f32 v[130:131], v[130:131], v[34:35] op_sel_hi:[1,0]
	v_pk_mul_f32 v[132:133], v[132:133], v[34:35] op_sel_hi:[1,0]
	v_pk_mul_f32 v[130:131], v[220:221], v[130:131]
	v_pk_mul_f32 v[132:133], v[222:223], v[132:133]
	v_cvt_pk_bf16_f32 v130, v130, v131
	v_cvt_pk_bf16_f32 v131, v132, v133
	v_pk_mul_f32 v[134:135], v[134:135], v[34:35] op_sel_hi:[1,0]
	v_pk_mul_f32 v[136:137], v[136:137], v[34:35] op_sel_hi:[1,0]
	v_pk_mul_f32 v[134:135], v[224:225], v[134:135]
	v_pk_mul_f32 v[136:137], v[226:227], v[136:137]
	v_cvt_pk_bf16_f32 v134, v134, v135
	v_cvt_pk_bf16_f32 v135, v136, v137
	v_pk_mul_f32 v[138:139], v[138:139], v[34:35] op_sel_hi:[1,0]
	v_pk_mul_f32 v[140:141], v[140:141], v[34:35] op_sel_hi:[1,0]
	v_pk_mul_f32 v[138:139], v[228:229], v[138:139]
	v_pk_mul_f32 v[140:141], v[230:231], v[140:141]
	v_cvt_pk_bf16_f32 v138, v138, v139
	v_cvt_pk_bf16_f32 v139, v140, v141
	v_pk_mul_f32 v[142:143], v[142:143], v[34:35] op_sel_hi:[1,0]
	v_pk_mul_f32 v[144:145], v[144:145], v[34:35] op_sel_hi:[1,0]
	v_pk_mul_f32 v[142:143], v[232:233], v[142:143]
	v_pk_mul_f32 v[144:145], v[234:235], v[144:145]
	v_cvt_pk_bf16_f32 v142, v142, v143
	v_cvt_pk_bf16_f32 v143, v144, v145
	global_store_dwordx2 v[4:5], v[130:131], off offset:-1024
	global_store_dwordx2 v[4:5], v[134:135], off offset:-512
	global_store_dwordx2 v[4:5], v[138:139], off
	global_store_dwordx2 v[4:5], v[142:143], off offset:512
	v_lshl_add_u64 v[4:5], v[4:5], 0, s[20:21]
	v_add_u32_e32 v0, s76, v0
	v_mov_b32_e32 v1, v237
	v_fmamk_f32 v1, v1, 0x3a800000, v154
	v_mul_f32_e32 v34, 0x4b800000, v1
	v_cmp_gt_f32_e32 vcc, s22, v1
	s_nop 1
	v_cndmask_b32_e32 v1, v1, v34, vcc
	v_rsq_f32_e32 v1, v1
	s_nop 0
	v_mul_f32_e32 v34, 0x45800000, v1
	v_cndmask_b32_e32 v34, v1, v34, vcc
	v_pk_mul_f32 v[146:147], v[146:147], v[34:35] op_sel_hi:[1,0]
	v_pk_mul_f32 v[148:149], v[148:149], v[34:35] op_sel_hi:[1,0]
	v_pk_mul_f32 v[146:147], v[220:221], v[146:147]
	v_pk_mul_f32 v[148:149], v[222:223], v[148:149]
	v_cvt_pk_bf16_f32 v146, v146, v147
	v_cvt_pk_bf16_f32 v147, v148, v149
; DI unsigned pk2(float a, float b) { f32x2 v = {a, b}; bf2_t r = __builtin_convertvector(v, bf2_t); return __builtin_bit_cast(unsigned, r); }
; DI void rms_row(const float* x, const float* gain, bf16_t* o, int lane) {
;     const f32x4* xr = (const f32x4*)x + lane; const f32x4* gr = (const f32x4*)gain + lane;
;     f32x4 v[4]; float s = 0.f;
; #pragma unroll
;     for (int j = 0; j < 4; ++j) { v[j] = xr[64 * j]; s += (v[j].x * v[j].x + v[j].y * v[j].y) + (v[j].z * v[j].z + v[j].w * v[j].w); }
;     const float rstd = rsqrtf(wave_sum(s) * (1.f / 1024.f) + 1e-6f);
;     u32x2* op = (u32x2*)o + lane;
; #pragma unroll
;     for (int j = 0; j < 4; ++j) { const f32x4 g = gr[64 * j]; u32x2 w; w.x = pk2(v[j].x * rstd * g.x, v[j].y * rstd * g.y); w.y = pk2(v[j].z * rstd * g.z, v[j].w * rstd * g.w); op[64 * j] = w; }
	v_pk_mul_f32 v[150:151], v[150:151], v[34:35] op_sel_hi:[1,0]
	v_pk_mul_f32 v[152:153], v[152:153], v[34:35] op_sel_hi:[1,0]
	v_pk_mul_f32 v[150:151], v[224:225], v[150:151]
	v_pk_mul_f32 v[152:153], v[226:227], v[152:153]
	v_cvt_pk_bf16_f32 v150, v150, v151
	v_cvt_pk_bf16_f32 v151, v152, v153
	v_pk_mul_f32 v[168:169], v[168:169], v[34:35] op_sel_hi:[1,0]
	v_pk_mul_f32 v[170:171], v[170:171], v[34:35] op_sel_hi:[1,0]
	v_pk_mul_f32 v[168:169], v[228:229], v[168:169]
	v_pk_mul_f32 v[170:171], v[230:231], v[170:171]
	v_cvt_pk_bf16_f32 v168, v168, v169
	v_cvt_pk_bf16_f32 v169, v170, v171
	v_pk_mul_f32 v[172:173], v[172:173], v[34:35] op_sel_hi:[1,0]
	v_pk_mul_f32 v[174:175], v[174:175], v[34:35] op_sel_hi:[1,0]
	v_pk_mul_f32 v[172:173], v[232:233], v[172:173]
	v_pk_mul_f32 v[174:175], v[234:235], v[174:175]
	v_cvt_pk_bf16_f32 v172, v172, v173
	v_cvt_pk_bf16_f32 v173, v174, v175
	global_store_dwordx2 v[4:5], v[146:147], off offset:-1024
	global_store_dwordx2 v[4:5], v[150:151], off offset:-512
	global_store_dwordx2 v[4:5], v[168:169], off
	global_store_dwordx2 v[4:5], v[172:173], off offset:512
	v_lshl_add_u64 v[4:5], v[4:5], 0, s[20:21]
	v_add_u32_e32 v0, s76, v0
	v_mov_b32_e32 v1, v238
	v_fmamk_f32 v1, v1, 0x3a800000, v154
	v_mul_f32_e32 v34, 0x4b800000, v1
	v_cmp_gt_f32_e32 vcc, s22, v1
	s_nop 1
	v_cndmask_b32_e32 v1, v1, v34, vcc
	v_rsq_f32_e32 v1, v1
	s_nop 0
	v_mul_f32_e32 v34, 0x45800000, v1
	v_cndmask_b32_e32 v34, v1, v34, vcc
	v_pk_mul_f32 v[176:177], v[176:177], v[34:35] op_sel_hi:[1,0]
	v_pk_mul_f32 v[178:179], v[178:179], v[34:35] op_sel_hi:[1,0]
	v_pk_mul_f32 v[176:177], v[220:221], v[176:177]
	v_pk_mul_f32 v[178:179], v[222:223], v[178:179]
	v_cvt_pk_bf16_f32 v176, v176, v177
	v_cvt_pk_bf16_f32 v177, v178, v179
	v_pk_mul_f32 v[180:181], v[180:181], v[34:35] op_sel_hi:[1,0]
	v_pk_mul_f32 v[182:183], v[182:183], v[34:35] op_sel_hi:[1,0]
	v_pk_mul_f32 v[180:181], v[224:225], v[180:181]
	v_pk_mul_f32 v[182:183], v[226:227], v[182:183]
	v_cvt_pk_bf16_f32 v180, v180, v181
	v_cvt_pk_bf16_f32 v181, v182, v183
	v_pk_mul_f32 v[184:185], v[184:185], v[34:35] op_sel_hi:[1,0]
	v_pk_mul_f32 v[186:187], v[186:187], v[34:35] op_sel_hi:[1,0]
	v_pk_mul_f32 v[184:185], v[228:229], v[184:185]
	v_pk_mul_f32 v[186:187], v[230:231], v[186:187]
	v_cvt_pk_bf16_f32 v184, v184, v185
	v_cvt_pk_bf16_f32 v185, v186, v187
	v_pk_mul_f32 v[196:197], v[196:197], v[34:35] op_sel_hi:[1,0]
	v_pk_mul_f32 v[198:199], v[198:199], v[34:35] op_sel_hi:[1,0]
	v_pk_mul_f32 v[196:197], v[232:233], v[196:197]
	v_pk_mul_f32 v[198:199], v[234:235], v[198:199]
	v_cvt_pk_bf16_f32 v196, v196, v197
	v_cvt_pk_bf16_f32 v197, v198, v199
	global_store_dwordx2 v[4:5], v[176:177], off offset:-1024
	global_store_dwordx2 v[4:5], v[180:181], off offset:-512
	global_store_dwordx2 v[4:5], v[184:185], off
	global_store_dwordx2 v[4:5], v[196:197], off offset:512
	v_lshl_add_u64 v[4:5], v[4:5], 0, s[20:21]
	v_add_u32_e32 v0, s76, v0
	v_mov_b32_e32 v1, v239
	v_fmamk_f32 v1, v1, 0x3a800000, v154
	v_mul_f32_e32 v34, 0x4b800000, v1
	v_cmp_gt_f32_e32 vcc, s22, v1
	s_nop 1
	v_cndmask_b32_e32 v1, v1, v34, vcc
	v_rsq_f32_e32 v1, v1
	s_nop 0
	v_mul_f32_e32 v34, 0x45800000, v1
	v_cndmask_b32_e32 v34, v1, v34, vcc
	v_pk_mul_f32 v[200:201], v[200:201], v[34:35] op_sel_hi:[1,0]
	v_pk_mul_f32 v[202:203], v[202:203], v[34:35] op_sel_hi:[1,0]
	v_pk_mul_f32 v[200:201], v[220:221], v[200:201]
	v_pk_mul_f32 v[202:203], v[222:223], v[202:203]
	v_cvt_pk_bf16_f32 v200, v200, v201
	v_cvt_pk_bf16_f32 v201, v202, v203
	v_pk_mul_f32 v[204:205], v[204:205], v[34:35] op_sel_hi:[1,0]
	v_pk_mul_f32 v[206:207], v[206:207], v[34:35] op_sel_hi:[1,0]
	v_pk_mul_f32 v[204:205], v[224:225], v[204:205]
	v_pk_mul_f32 v[206:207], v[226:227], v[206:207]
	v_cvt_pk_bf16_f32 v204, v204, v205
	v_cvt_pk_bf16_f32 v205, v206, v207
	v_pk_mul_f32 v[212:213], v[212:213], v[34:35] op_sel_hi:[1,0]
	v_pk_mul_f32 v[214:215], v[214:215], v[34:35] op_sel_hi:[1,0]
	v_pk_mul_f32 v[212:213], v[228:229], v[212:213]
	v_pk_mul_f32 v[214:215], v[230:231], v[214:215]
	v_cvt_pk_bf16_f32 v212, v212, v213
	v_cvt_pk_bf16_f32 v213, v214, v215
	v_pk_mul_f32 v[216:217], v[216:217], v[34:35] op_sel_hi:[1,0]
	v_pk_mul_f32 v[218:219], v[218:219], v[34:35] op_sel_hi:[1,0]
	v_pk_mul_f32 v[216:217], v[232:233], v[216:217]
	v_pk_mul_f32 v[218:219], v[234:235], v[218:219]
	v_cvt_pk_bf16_f32 v216, v216, v217
	v_cvt_pk_bf16_f32 v217, v218, v219
	global_store_dwordx2 v[4:5], v[200:201], off offset:-1024
	global_store_dwordx2 v[4:5], v[204:205], off offset:-512
	global_store_dwordx2 v[4:5], v[212:213], off
	global_store_dwordx2 v[4:5], v[216:217], off offset:512
	v_lshl_add_u64 v[4:5], v[4:5], 0, s[20:21]
	v_add_u32_e32 v0, s76, v0
	global_load_dwordx4 v[130:133], v[6:7], off offset:-3072
	global_load_dwordx4 v[134:137], v[6:7], off offset:-2048
	global_load_dwordx4 v[138:141], v[6:7], off offset:-1024
	global_load_dwordx4 v[142:145], v[6:7], off
	v_lshl_add_u64 v[6:7], v[6:7], 0, s[24:25]
	global_load_dwordx4 v[146:149], v[6:7], off offset:-3072
	global_load_dwordx4 v[150:153], v[6:7], off offset:-2048
	global_load_dwordx4 v[168:171], v[6:7], off offset:-1024
	global_load_dwordx4 v[172:175], v[6:7], off
	v_lshl_add_u64 v[6:7], v[6:7], 0, s[24:25]
	global_load_dwordx4 v[176:179], v[6:7], off offset:-3072
	global_load_dwordx4 v[180:183], v[6:7], off offset:-2048
	global_load_dwordx4 v[184:187], v[6:7], off offset:-1024
	global_load_dwordx4 v[196:199], v[6:7], off
	v_lshl_add_u64 v[6:7], v[6:7], 0, s[24:25]
	global_load_dwordx4 v[200:203], v[6:7], off offset:-3072
	global_load_dwordx4 v[204:207], v[6:7], off offset:-2048
	global_load_dwordx4 v[212:215], v[6:7], off offset:-1024
	global_load_dwordx4 v[216:219], v[6:7], off
	v_lshl_add_u64 v[6:7], v[6:7], 0, s[24:25]
	s_waitcnt vmcnt(28)
; DI float wave_sum(float v) {
; #pragma unroll
;     for (int o = 1; o < 64; o <<= 1) v += __shfl_xor(v, o);
;     return v;
; DI void rms_row(const float* x, const float* gain, bf16_t* o, int lane) {
;     ...
;     for (int j = 0; j < 4; ++j) { v[j] = xr[64 * j]; s += (v[j].x * v[j].x + v[j].y * v[j].y) + (v[j].z * v[j].z + v[j].w * v[j].w); }
;     const float rstd = rsqrtf(wave_sum(s) * (1.f / 1024.f) + 1e-6f);
	v_pk_mul_f32 v[34:35], v[66:67], v[66:67]
	v_pk_mul_f32 v[36:37], v[64:65], v[64:65]
	v_pk_mul_f32 v[38:39], v[70:71], v[70:71]
	v_pk_mul_f32 v[40:41], v[68:69], v[68:69]
	v_pk_mov_b32 v[46:47], v[36:37], v[34:35] op_sel:[1,0]
	v_mov_b32_e32 v37, v35
	v_pk_mov_b32 v[34:35], v[40:41], v[38:39] op_sel:[1,0]
	v_mov_b32_e32 v41, v39
	v_mul_f32_e32 v45, v77, v77
	v_mul_f32_e32 v42, v73, v73
	v_mul_f32_e32 v44, v75, v75
	v_pk_add_f32 v[36:37], v[46:47], v[36:37]
	v_pk_add_f32 v[34:35], v[34:35], v[40:41]
	v_mul_f32_e32 v1, v76, v76
	v_mul_f32_e32 v48, v78, v78
	v_mul_f32_e32 v49, v79, v79
	v_pk_fma_f32 v[38:39], v[72:73], v[72:73], v[42:43] op_sel_hi:[1,1,0]
	v_pk_fma_f32 v[42:43], v[74:75], v[74:75], v[44:45] op_sel_hi:[1,1,0]
	v_pk_add_f32 v[36:37], v[36:37], v[36:37] op_sel:[0,1] op_sel_hi:[1,0]
	v_pk_add_f32 v[34:35], v[34:35], v[34:35] op_sel:[0,1] op_sel_hi:[1,0]
	v_mov_b32_e32 v39, v48
	v_mov_b32_e32 v43, v49
	v_mov_b32_e32 v37, v1
	v_mov_b32_e32 v35, v45
	v_pk_add_f32 v[38:39], v[38:39], v[42:43]
	v_pk_add_f32 v[34:35], v[36:37], v[34:35]
	s_nop 0
	v_pk_add_f32 v[34:35], v[34:35], v[38:39]
	s_nop 0
	v_add_f32_e32 v1, v34, v35
	v_mov_b32_e32 v236, v1
	s_waitcnt vmcnt(24)
	v_pk_mul_f32 v[34:35], v[82:83], v[82:83]
	v_pk_mul_f32 v[36:37], v[80:81], v[80:81]
	v_pk_mul_f32 v[38:39], v[86:87], v[86:87]
	v_pk_mul_f32 v[40:41], v[84:85], v[84:85]
	v_pk_mov_b32 v[46:47], v[36:37], v[34:35] op_sel:[1,0]
	v_mov_b32_e32 v37, v35
	v_pk_mov_b32 v[34:35], v[40:41], v[38:39] op_sel:[1,0]
	v_mov_b32_e32 v41, v39
	v_mul_f32_e32 v45, v93, v93
	v_mul_f32_e32 v42, v89, v89
	v_mul_f32_e32 v44, v91, v91
	v_pk_add_f32 v[36:37], v[46:47], v[36:37]
	v_pk_add_f32 v[34:35], v[34:35], v[40:41]
	v_mul_f32_e32 v1, v92, v92
	v_mul_f32_e32 v48, v94, v94
	v_mul_f32_e32 v49, v95, v95
	v_pk_fma_f32 v[38:39], v[88:89], v[88:89], v[42:43] op_sel_hi:[1,1,0]
	v_pk_fma_f32 v[42:43], v[90:91], v[90:91], v[44:45] op_sel_hi:[1,1,0]
	v_pk_add_f32 v[36:37], v[36:37], v[36:37] op_sel:[0,1] op_sel_hi:[1,0]
	v_pk_add_f32 v[34:35], v[34:35], v[34:35] op_sel:[0,1] op_sel_hi:[1,0]
	v_mov_b32_e32 v39, v48
	v_mov_b32_e32 v43, v49
	v_mov_b32_e32 v37, v1
	v_mov_b32_e32 v35, v45
	v_pk_add_f32 v[38:39], v[38:39], v[42:43]
	v_pk_add_f32 v[34:35], v[36:37], v[34:35]
	s_nop 0
	v_pk_add_f32 v[34:35], v[34:35], v[38:39]
	s_nop 0
	v_add_f32_e32 v1, v34, v35
	v_mov_b32_e32 v237, v1
	s_waitcnt vmcnt(20)
	v_pk_mul_f32 v[34:35], v[98:99], v[98:99]
	v_pk_mul_f32 v[36:37], v[96:97], v[96:97]
	v_pk_mul_f32 v[38:39], v[102:103], v[102:103]
	v_pk_mul_f32 v[40:41], v[100:101], v[100:101]
	v_pk_mov_b32 v[46:47], v[36:37], v[34:35] op_sel:[1,0]
	v_mov_b32_e32 v37, v35
	v_pk_mov_b32 v[34:35], v[40:41], v[38:39] op_sel:[1,0]
	v_mov_b32_e32 v41, v39
	v_mul_f32_e32 v45, v109, v109
	v_mul_f32_e32 v42, v105, v105
	v_mul_f32_e32 v44, v107, v107
	v_pk_add_f32 v[36:37], v[46:47], v[36:37]
	v_pk_add_f32 v[34:35], v[34:35], v[40:41]
	v_mul_f32_e32 v1, v108, v108
	v_mul_f32_e32 v48, v110, v110
	v_mul_f32_e32 v49, v111, v111
	v_pk_fma_f32 v[38:39], v[104:105], v[104:105], v[42:43] op_sel_hi:[1,1,0]
	v_pk_fma_f32 v[42:43], v[106:107], v[106:107], v[44:45] op_sel_hi:[1,1,0]
	v_pk_add_f32 v[36:37], v[36:37], v[36:37] op_sel:[0,1] op_sel_hi:[1,0]
	v_pk_add_f32 v[34:35], v[34:35], v[34:35] op_sel:[0,1] op_sel_hi:[1,0]
	v_mov_b32_e32 v39, v48
	v_mov_b32_e32 v43, v49
	v_mov_b32_e32 v37, v1
	v_mov_b32_e32 v35, v45
	v_pk_add_f32 v[38:39], v[38:39], v[42:43]
	v_pk_add_f32 v[34:35], v[36:37], v[34:35]
	s_nop 0
	v_pk_add_f32 v[34:35], v[34:35], v[38:39]
	s_nop 0
	v_add_f32_e32 v1, v34, v35
	v_mov_b32_e32 v238, v1
	s_waitcnt vmcnt(16)
	v_pk_mul_f32 v[34:35], v[114:115], v[114:115]
	v_pk_mul_f32 v[36:37], v[112:113], v[112:113]
	v_pk_mul_f32 v[38:39], v[118:119], v[118:119]
	v_pk_mul_f32 v[40:41], v[116:117], v[116:117]
	v_pk_mov_b32 v[46:47], v[36:37], v[34:35] op_sel:[1,0]
	v_mov_b32_e32 v37, v35
	v_pk_mov_b32 v[34:35], v[40:41], v[38:39] op_sel:[1,0]
	v_mov_b32_e32 v41, v39
	v_mul_f32_e32 v45, v125, v125
	v_mul_f32_e32 v42, v121, v121
	v_mul_f32_e32 v44, v123, v123
	v_pk_add_f32 v[36:37], v[46:47], v[36:37]
	v_pk_add_f32 v[34:35], v[34:35], v[40:41]
	v_mul_f32_e32 v1, v124, v124
	v_mul_f32_e32 v48, v126, v126
	v_mul_f32_e32 v49, v127, v127
	v_pk_fma_f32 v[38:39], v[120:121], v[120:121], v[42:43] op_sel_hi:[1,1,0]
	v_pk_fma_f32 v[42:43], v[122:123], v[122:123], v[44:45] op_sel_hi:[1,1,0]
	v_pk_add_f32 v[36:37], v[36:37], v[36:37] op_sel:[0,1] op_sel_hi:[1,0]
	v_pk_add_f32 v[34:35], v[34:35], v[34:35] op_sel:[0,1] op_sel_hi:[1,0]
	v_mov_b32_e32 v39, v48
	v_mov_b32_e32 v43, v49
	v_mov_b32_e32 v37, v1
	v_mov_b32_e32 v35, v45
	v_pk_add_f32 v[38:39], v[38:39], v[42:43]
	v_pk_add_f32 v[34:35], v[36:37], v[34:35]
	s_nop 0
	v_pk_add_f32 v[34:35], v[34:35], v[38:39]
	s_nop 0
	v_add_f32_e32 v1, v34, v35
	v_mov_b32_e32 v239, v1
	ds_bpermute_b32 v240, v8, v236
	ds_bpermute_b32 v241, v8, v237
	ds_bpermute_b32 v242, v8, v238
	ds_bpermute_b32 v243, v8, v239
	s_waitcnt lgkmcnt(3)
	v_add_f32_e32 v236, v236, v240
	s_waitcnt lgkmcnt(2)
	v_add_f32_e32 v237, v237, v241
	s_waitcnt lgkmcnt(1)
	v_add_f32_e32 v238, v238, v242
	s_waitcnt lgkmcnt(0)
	v_add_f32_e32 v239, v239, v243
	ds_bpermute_b32 v240, v9, v236
	ds_bpermute_b32 v241, v9, v237
	ds_bpermute_b32 v242, v9, v238
	ds_bpermute_b32 v243, v9, v239
	s_waitcnt lgkmcnt(3)
	v_add_f32_e32 v236, v236, v240
	s_waitcnt lgkmcnt(2)
	v_add_f32_e32 v237, v237, v241
	s_waitcnt lgkmcnt(1)
	v_add_f32_e32 v238, v238, v242
	s_waitcnt lgkmcnt(0)
	v_add_f32_e32 v239, v239, v243
	ds_bpermute_b32 v240, v10, v236
	ds_bpermute_b32 v241, v10, v237
	ds_bpermute_b32 v242, v10, v238
	ds_bpermute_b32 v243, v10, v239
	s_waitcnt lgkmcnt(3)
; DI unsigned pk2(float a, float b) { f32x2 v = {a, b}; bf2_t r = __builtin_convertvector(v, bf2_t); return __builtin_bit_cast(unsigned, r); }
; DI void rms_row(const float* x, const float* gain, bf16_t* o, int lane) {
;     ...
;     const float rstd = rsqrtf(wave_sum(s) * (1.f / 1024.f) + 1e-6f);
;     u32x2* op = (u32x2*)o + lane;
; #pragma unroll
;     for (int j = 0; j < 4; ++j) { const f32x4 g = gr[64 * j]; u32x2 w; w.x = pk2(v[j].x * rstd * g.x, v[j].y * rstd * g.y); w.y = pk2(v[j].z * rstd * g.z, v[j].w * rstd * g.w); op[64 * j] = w; }
	v_add_f32_e32 v236, v236, v240
	s_waitcnt lgkmcnt(2)
	v_add_f32_e32 v237, v237, v241
	s_waitcnt lgkmcnt(1)
	v_add_f32_e32 v238, v238, v242
	s_waitcnt lgkmcnt(0)
	v_add_f32_e32 v239, v239, v243
	ds_bpermute_b32 v240, v11, v236
	ds_bpermute_b32 v241, v11, v237
	ds_bpermute_b32 v242, v11, v238
	ds_bpermute_b32 v243, v11, v239
	s_waitcnt lgkmcnt(3)
	v_add_f32_e32 v236, v236, v240
	s_waitcnt lgkmcnt(2)
	v_add_f32_e32 v237, v237, v241
	s_waitcnt lgkmcnt(1)
	v_add_f32_e32 v238, v238, v242
	s_waitcnt lgkmcnt(0)
	v_add_f32_e32 v239, v239, v243
	ds_bpermute_b32 v240, v12, v236
	ds_bpermute_b32 v241, v12, v237
	ds_bpermute_b32 v242, v12, v238
	ds_bpermute_b32 v243, v12, v239
	s_waitcnt lgkmcnt(3)
	v_add_f32_e32 v236, v236, v240
	s_waitcnt lgkmcnt(2)
	v_add_f32_e32 v237, v237, v241
	s_waitcnt lgkmcnt(1)
	v_add_f32_e32 v238, v238, v242
	s_waitcnt lgkmcnt(0)
	v_add_f32_e32 v239, v239, v243
	ds_bpermute_b32 v240, v13, v236
	ds_bpermute_b32 v241, v13, v237
	ds_bpermute_b32 v242, v13, v238
	ds_bpermute_b32 v243, v13, v239
	s_waitcnt lgkmcnt(3)
	v_add_f32_e32 v236, v236, v240
	s_waitcnt lgkmcnt(2)
	v_add_f32_e32 v237, v237, v241
	s_waitcnt lgkmcnt(1)
	v_add_f32_e32 v238, v238, v242
	s_waitcnt lgkmcnt(0)
	v_add_f32_e32 v239, v239, v243
	v_mov_b32_e32 v1, v236
	v_fmamk_f32 v1, v1, 0x3a800000, v154
	v_mul_f32_e32 v34, 0x4b800000, v1
	v_cmp_gt_f32_e32 vcc, s22, v1
	s_nop 1
	v_cndmask_b32_e32 v1, v1, v34, vcc
	v_rsq_f32_e32 v1, v1
	s_nop 0
	v_mul_f32_e32 v34, 0x45800000, v1
	v_cndmask_b32_e32 v34, v1, v34, vcc
	v_pk_mul_f32 v[64:65], v[64:65], v[34:35] op_sel_hi:[1,0]
	v_pk_mul_f32 v[66:67], v[66:67], v[34:35] op_sel_hi:[1,0]
	v_pk_mul_f32 v[64:65], v[220:221], v[64:65]
	v_pk_mul_f32 v[66:67], v[222:223], v[66:67]
	v_cvt_pk_bf16_f32 v64, v64, v65
	v_cvt_pk_bf16_f32 v65, v66, v67
	v_pk_mul_f32 v[68:69], v[68:69], v[34:35] op_sel_hi:[1,0]
	v_pk_mul_f32 v[70:71], v[70:71], v[34:35] op_sel_hi:[1,0]
	v_pk_mul_f32 v[68:69], v[224:225], v[68:69]
	v_pk_mul_f32 v[70:71], v[226:227], v[70:71]
	v_cvt_pk_bf16_f32 v68, v68, v69
	v_cvt_pk_bf16_f32 v69, v70, v71
	v_pk_mul_f32 v[72:73], v[72:73], v[34:35] op_sel_hi:[1,0]
	v_pk_mul_f32 v[74:75], v[74:75], v[34:35] op_sel_hi:[1,0]
	v_pk_mul_f32 v[72:73], v[228:229], v[72:73]
	v_pk_mul_f32 v[74:75], v[230:231], v[74:75]
	v_cvt_pk_bf16_f32 v72, v72, v73
	v_cvt_pk_bf16_f32 v73, v74, v75
	v_pk_mul_f32 v[76:77], v[76:77], v[34:35] op_sel_hi:[1,0]
	v_pk_mul_f32 v[78:79], v[78:79], v[34:35] op_sel_hi:[1,0]
	v_pk_mul_f32 v[76:77], v[232:233], v[76:77]
	v_pk_mul_f32 v[78:79], v[234:235], v[78:79]
	v_cvt_pk_bf16_f32 v76, v76, v77
	v_cvt_pk_bf16_f32 v77, v78, v79
	global_store_dwordx2 v[4:5], v[64:65], off offset:-1024
	global_store_dwordx2 v[4:5], v[68:69], off offset:-512
	global_store_dwordx2 v[4:5], v[72:73], off
	global_store_dwordx2 v[4:5], v[76:77], off offset:512
	v_lshl_add_u64 v[4:5], v[4:5], 0, s[20:21]
	v_add_u32_e32 v0, s76, v0
	v_mov_b32_e32 v1, v237
	v_fmamk_f32 v1, v1, 0x3a800000, v154
	v_mul_f32_e32 v34, 0x4b800000, v1
	v_cmp_gt_f32_e32 vcc, s22, v1
	s_nop 1
	v_cndmask_b32_e32 v1, v1, v34, vcc
	v_rsq_f32_e32 v1, v1
	s_nop 0
	v_mul_f32_e32 v34, 0x45800000, v1
	v_cndmask_b32_e32 v34, v1, v34, vcc
	v_pk_mul_f32 v[80:81], v[80:81], v[34:35] op_sel_hi:[1,0]
	v_pk_mul_f32 v[82:83], v[82:83], v[34:35] op_sel_hi:[1,0]
	v_pk_mul_f32 v[80:81], v[220:221], v[80:81]
	v_pk_mul_f32 v[82:83], v[222:223], v[82:83]
	v_cvt_pk_bf16_f32 v80, v80, v81
	v_cvt_pk_bf16_f32 v81, v82, v83
	v_pk_mul_f32 v[84:85], v[84:85], v[34:35] op_sel_hi:[1,0]
	v_pk_mul_f32 v[86:87], v[86:87], v[34:35] op_sel_hi:[1,0]
	v_pk_mul_f32 v[84:85], v[224:225], v[84:85]
	v_pk_mul_f32 v[86:87], v[226:227], v[86:87]
	v_cvt_pk_bf16_f32 v84, v84, v85
	v_cvt_pk_bf16_f32 v85, v86, v87
	v_pk_mul_f32 v[88:89], v[88:89], v[34:35] op_sel_hi:[1,0]
	v_pk_mul_f32 v[90:91], v[90:91], v[34:35] op_sel_hi:[1,0]
	v_pk_mul_f32 v[88:89], v[228:229], v[88:89]
	v_pk_mul_f32 v[90:91], v[230:231], v[90:91]
	v_cvt_pk_bf16_f32 v88, v88, v89
	v_cvt_pk_bf16_f32 v89, v90, v91
	v_pk_mul_f32 v[92:93], v[92:93], v[34:35] op_sel_hi:[1,0]
	v_pk_mul_f32 v[94:95], v[94:95], v[34:35] op_sel_hi:[1,0]
	v_pk_mul_f32 v[92:93], v[232:233], v[92:93]
	v_pk_mul_f32 v[94:95], v[234:235], v[94:95]
	v_cvt_pk_bf16_f32 v92, v92, v93
	v_cvt_pk_bf16_f32 v93, v94, v95
	global_store_dwordx2 v[4:5], v[80:81], off offset:-1024
	global_store_dwordx2 v[4:5], v[84:85], off offset:-512
	global_store_dwordx2 v[4:5], v[88:89], off
	global_store_dwordx2 v[4:5], v[92:93], off offset:512
	v_lshl_add_u64 v[4:5], v[4:5], 0, s[20:21]
	v_add_u32_e32 v0, s76, v0
	v_mov_b32_e32 v1, v238
	v_fmamk_f32 v1, v1, 0x3a800000, v154
	v_mul_f32_e32 v34, 0x4b800000, v1
	v_cmp_gt_f32_e32 vcc, s22, v1
	s_nop 1
	v_cndmask_b32_e32 v1, v1, v34, vcc
	v_rsq_f32_e32 v1, v1
	s_nop 0
	v_mul_f32_e32 v34, 0x45800000, v1
	v_cndmask_b32_e32 v34, v1, v34, vcc
	v_pk_mul_f32 v[96:97], v[96:97], v[34:35] op_sel_hi:[1,0]
	v_pk_mul_f32 v[98:99], v[98:99], v[34:35] op_sel_hi:[1,0]
	v_pk_mul_f32 v[96:97], v[220:221], v[96:97]
	v_pk_mul_f32 v[98:99], v[222:223], v[98:99]
	v_cvt_pk_bf16_f32 v96, v96, v97
	v_cvt_pk_bf16_f32 v97, v98, v99
	v_pk_mul_f32 v[100:101], v[100:101], v[34:35] op_sel_hi:[1,0]
	v_pk_mul_f32 v[102:103], v[102:103], v[34:35] op_sel_hi:[1,0]
	v_pk_mul_f32 v[100:101], v[224:225], v[100:101]
	v_pk_mul_f32 v[102:103], v[226:227], v[102:103]
	v_cvt_pk_bf16_f32 v100, v100, v101
	v_cvt_pk_bf16_f32 v101, v102, v103
	v_pk_mul_f32 v[104:105], v[104:105], v[34:35] op_sel_hi:[1,0]
	v_pk_mul_f32 v[106:107], v[106:107], v[34:35] op_sel_hi:[1,0]
	v_pk_mul_f32 v[104:105], v[228:229], v[104:105]
	v_pk_mul_f32 v[106:107], v[230:231], v[106:107]
	v_cvt_pk_bf16_f32 v104, v104, v105
; DI unsigned pk2(float a, float b) { f32x2 v = {a, b}; bf2_t r = __builtin_convertvector(v, bf2_t); return __builtin_bit_cast(unsigned, r); }
; DI void rms_row(const float* x, const float* gain, bf16_t* o, int lane) {
;     ...
;     for (int j = 0; j < 4; ++j) { v[j] = xr[64 * j]; s += (v[j].x * v[j].x + v[j].y * v[j].y) + (v[j].z * v[j].z + v[j].w * v[j].w); }
;     const float rstd = rsqrtf(wave_sum(s) * (1.f / 1024.f) + 1e-6f);
;     u32x2* op = (u32x2*)o + lane;
; #pragma unroll
;     for (int j = 0; j < 4; ++j) { const f32x4 g = gr[64 * j]; u32x2 w; w.x = pk2(v[j].x * rstd * g.x, v[j].y * rstd * g.y); w.y = pk2(v[j].z * rstd * g.z, v[j].w * rstd * g.w); op[64 * j] = w; }
	v_cvt_pk_bf16_f32 v105, v106, v107
	v_pk_mul_f32 v[108:109], v[108:109], v[34:35] op_sel_hi:[1,0]
	v_pk_mul_f32 v[110:111], v[110:111], v[34:35] op_sel_hi:[1,0]
	v_pk_mul_f32 v[108:109], v[232:233], v[108:109]
	v_pk_mul_f32 v[110:111], v[234:235], v[110:111]
	v_cvt_pk_bf16_f32 v108, v108, v109
	v_cvt_pk_bf16_f32 v109, v110, v111
	global_store_dwordx2 v[4:5], v[96:97], off offset:-1024
	global_store_dwordx2 v[4:5], v[100:101], off offset:-512
	global_store_dwordx2 v[4:5], v[104:105], off
	global_store_dwordx2 v[4:5], v[108:109], off offset:512
	v_lshl_add_u64 v[4:5], v[4:5], 0, s[20:21]
	v_add_u32_e32 v0, s76, v0
	v_mov_b32_e32 v1, v239
	v_fmamk_f32 v1, v1, 0x3a800000, v154
	v_mul_f32_e32 v34, 0x4b800000, v1
	v_cmp_gt_f32_e32 vcc, s22, v1
	s_nop 1
	v_cndmask_b32_e32 v1, v1, v34, vcc
	v_rsq_f32_e32 v1, v1
	s_nop 0
	v_mul_f32_e32 v34, 0x45800000, v1
	v_cndmask_b32_e32 v34, v1, v34, vcc
	v_pk_mul_f32 v[112:113], v[112:113], v[34:35] op_sel_hi:[1,0]
	v_pk_mul_f32 v[114:115], v[114:115], v[34:35] op_sel_hi:[1,0]
	v_pk_mul_f32 v[112:113], v[220:221], v[112:113]
	v_pk_mul_f32 v[114:115], v[222:223], v[114:115]
	v_cvt_pk_bf16_f32 v112, v112, v113
	v_cvt_pk_bf16_f32 v113, v114, v115
	v_pk_mul_f32 v[116:117], v[116:117], v[34:35] op_sel_hi:[1,0]
	v_pk_mul_f32 v[118:119], v[118:119], v[34:35] op_sel_hi:[1,0]
	v_pk_mul_f32 v[116:117], v[224:225], v[116:117]
	v_pk_mul_f32 v[118:119], v[226:227], v[118:119]
	v_cvt_pk_bf16_f32 v116, v116, v117
	v_cvt_pk_bf16_f32 v117, v118, v119
	v_pk_mul_f32 v[120:121], v[120:121], v[34:35] op_sel_hi:[1,0]
	v_pk_mul_f32 v[122:123], v[122:123], v[34:35] op_sel_hi:[1,0]
	v_pk_mul_f32 v[120:121], v[228:229], v[120:121]
	v_pk_mul_f32 v[122:123], v[230:231], v[122:123]
	v_cvt_pk_bf16_f32 v120, v120, v121
	v_cvt_pk_bf16_f32 v121, v122, v123
	v_pk_mul_f32 v[124:125], v[124:125], v[34:35] op_sel_hi:[1,0]
	v_pk_mul_f32 v[126:127], v[126:127], v[34:35] op_sel_hi:[1,0]
	v_pk_mul_f32 v[124:125], v[232:233], v[124:125]
	v_pk_mul_f32 v[126:127], v[234:235], v[126:127]
	v_cvt_pk_bf16_f32 v124, v124, v125
	v_cvt_pk_bf16_f32 v125, v126, v127
	global_store_dwordx2 v[4:5], v[112:113], off offset:-1024
	global_store_dwordx2 v[4:5], v[116:117], off offset:-512
	global_store_dwordx2 v[4:5], v[120:121], off
	global_store_dwordx2 v[4:5], v[124:125], off offset:512
	v_lshl_add_u64 v[4:5], v[4:5], 0, s[20:21]
	v_add_u32_e32 v0, s76, v0
	s_waitcnt vmcnt(12)
	v_pk_mul_f32 v[34:35], v[132:133], v[132:133]
	v_pk_mul_f32 v[36:37], v[130:131], v[130:131]
	v_pk_mul_f32 v[38:39], v[136:137], v[136:137]
	v_pk_mul_f32 v[40:41], v[134:135], v[134:135]
	v_pk_mov_b32 v[46:47], v[36:37], v[34:35] op_sel:[1,0]
	v_mov_b32_e32 v37, v35
	v_pk_mov_b32 v[34:35], v[40:41], v[38:39] op_sel:[1,0]
	v_mov_b32_e32 v41, v39
	v_mul_f32_e32 v45, v143, v143
	v_mul_f32_e32 v42, v139, v139
	v_mul_f32_e32 v44, v141, v141
	v_pk_add_f32 v[36:37], v[46:47], v[36:37]
	v_pk_add_f32 v[34:35], v[34:35], v[40:41]
	v_mul_f32_e32 v1, v142, v142
	v_mul_f32_e32 v48, v144, v144
	v_mul_f32_e32 v49, v145, v145
	v_pk_fma_f32 v[38:39], v[138:139], v[138:139], v[42:43] op_sel_hi:[1,1,0]
	v_pk_fma_f32 v[42:43], v[140:141], v[140:141], v[44:45] op_sel_hi:[1,1,0]
	v_pk_add_f32 v[36:37], v[36:37], v[36:37] op_sel:[0,1] op_sel_hi:[1,0]
	v_pk_add_f32 v[34:35], v[34:35], v[34:35] op_sel:[0,1] op_sel_hi:[1,0]
	v_mov_b32_e32 v39, v48
	v_mov_b32_e32 v43, v49
	v_mov_b32_e32 v37, v1
	v_mov_b32_e32 v35, v45
	v_pk_add_f32 v[38:39], v[38:39], v[42:43]
	v_pk_add_f32 v[34:35], v[36:37], v[34:35]
	s_nop 0
	v_pk_add_f32 v[34:35], v[34:35], v[38:39]
	s_nop 0
	v_add_f32_e32 v1, v34, v35
	v_mov_b32_e32 v236, v1
	s_waitcnt vmcnt(8)
	v_pk_mul_f32 v[34:35], v[148:149], v[148:149]
	v_pk_mul_f32 v[36:37], v[146:147], v[146:147]
	v_pk_mul_f32 v[38:39], v[152:153], v[152:153]
	v_pk_mul_f32 v[40:41], v[150:151], v[150:151]
	v_pk_mov_b32 v[46:47], v[36:37], v[34:35] op_sel:[1,0]
	v_mov_b32_e32 v37, v35
	v_pk_mov_b32 v[34:35], v[40:41], v[38:39] op_sel:[1,0]
	v_mov_b32_e32 v41, v39
	v_mul_f32_e32 v45, v173, v173
	v_mul_f32_e32 v42, v169, v169
	v_mul_f32_e32 v44, v171, v171
	v_pk_add_f32 v[36:37], v[46:47], v[36:37]
	v_pk_add_f32 v[34:35], v[34:35], v[40:41]
	v_mul_f32_e32 v1, v172, v172
	v_mul_f32_e32 v48, v174, v174
	v_mul_f32_e32 v49, v175, v175
	v_pk_fma_f32 v[38:39], v[168:169], v[168:169], v[42:43] op_sel_hi:[1,1,0]
	v_pk_fma_f32 v[42:43], v[170:171], v[170:171], v[44:45] op_sel_hi:[1,1,0]
	v_pk_add_f32 v[36:37], v[36:37], v[36:37] op_sel:[0,1] op_sel_hi:[1,0]
	v_pk_add_f32 v[34:35], v[34:35], v[34:35] op_sel:[0,1] op_sel_hi:[1,0]
	v_mov_b32_e32 v39, v48
	v_mov_b32_e32 v43, v49
	v_mov_b32_e32 v37, v1
	v_mov_b32_e32 v35, v45
	v_pk_add_f32 v[38:39], v[38:39], v[42:43]
	v_pk_add_f32 v[34:35], v[36:37], v[34:35]
	s_nop 0
	v_pk_add_f32 v[34:35], v[34:35], v[38:39]
	s_nop 0
	v_add_f32_e32 v1, v34, v35
	v_mov_b32_e32 v237, v1
	s_waitcnt vmcnt(4)
	v_pk_mul_f32 v[34:35], v[178:179], v[178:179]
	v_pk_mul_f32 v[36:37], v[176:177], v[176:177]
	v_pk_mul_f32 v[38:39], v[182:183], v[182:183]
	v_pk_mul_f32 v[40:41], v[180:181], v[180:181]
	v_pk_mov_b32 v[46:47], v[36:37], v[34:35] op_sel:[1,0]
	v_mov_b32_e32 v37, v35
	v_pk_mov_b32 v[34:35], v[40:41], v[38:39] op_sel:[1,0]
	v_mov_b32_e32 v41, v39
	v_mul_f32_e32 v45, v197, v197
	v_mul_f32_e32 v42, v185, v185
	v_mul_f32_e32 v44, v187, v187
	v_pk_add_f32 v[36:37], v[46:47], v[36:37]
	v_pk_add_f32 v[34:35], v[34:35], v[40:41]
	v_mul_f32_e32 v1, v196, v196
	v_mul_f32_e32 v48, v198, v198
	v_mul_f32_e32 v49, v199, v199
	v_pk_fma_f32 v[38:39], v[184:185], v[184:185], v[42:43] op_sel_hi:[1,1,0]
	v_pk_fma_f32 v[42:43], v[186:187], v[186:187], v[44:45] op_sel_hi:[1,1,0]
	v_pk_add_f32 v[36:37], v[36:37], v[36:37] op_sel:[0,1] op_sel_hi:[1,0]
	v_pk_add_f32 v[34:35], v[34:35], v[34:35] op_sel:[0,1] op_sel_hi:[1,0]
	v_mov_b32_e32 v39, v48
	v_mov_b32_e32 v43, v49
	v_mov_b32_e32 v37, v1
	v_mov_b32_e32 v35, v45
	v_pk_add_f32 v[38:39], v[38:39], v[42:43]
	v_pk_add_f32 v[34:35], v[36:37], v[34:35]
	s_nop 0
	v_pk_add_f32 v[34:35], v[34:35], v[38:39]
	s_nop 0
	v_add_f32_e32 v1, v34, v35
	v_mov_b32_e32 v238, v1
	s_waitcnt vmcnt(0)
; DI unsigned pk2(float a, float b) { f32x2 v = {a, b}; bf2_t r = __builtin_convertvector(v, bf2_t); return __builtin_bit_cast(unsigned, r); }
; DI float wave_sum(float v) {
; #pragma unroll
;     for (int o = 1; o < 64; o <<= 1) v += __shfl_xor(v, o);
;     return v;
; DI void rms_row(const float* x, const float* gain, bf16_t* o, int lane) {
;     ...
;     for (int j = 0; j < 4; ++j) { v[j] = xr[64 * j]; s += (v[j].x * v[j].x + v[j].y * v[j].y) + (v[j].z * v[j].z + v[j].w * v[j].w); }
;     const float rstd = rsqrtf(wave_sum(s) * (1.f / 1024.f) + 1e-6f);
;     u32x2* op = (u32x2*)o + lane;
; #pragma unroll
;     for (int j = 0; j < 4; ++j) { const f32x4 g = gr[64 * j]; u32x2 w; w.x = pk2(v[j].x * rstd * g.x, v[j].y * rstd * g.y); w.y = pk2(v[j].z * rstd * g.z, v[j].w * rstd * g.w); op[64 * j] = w; }
	v_pk_mul_f32 v[34:35], v[202:203], v[202:203]
	v_pk_mul_f32 v[36:37], v[200:201], v[200:201]
	v_pk_mul_f32 v[38:39], v[206:207], v[206:207]
	v_pk_mul_f32 v[40:41], v[204:205], v[204:205]
	v_pk_mov_b32 v[46:47], v[36:37], v[34:35] op_sel:[1,0]
	v_mov_b32_e32 v37, v35
	v_pk_mov_b32 v[34:35], v[40:41], v[38:39] op_sel:[1,0]
	v_mov_b32_e32 v41, v39
	v_mul_f32_e32 v45, v217, v217
	v_mul_f32_e32 v42, v213, v213
	v_mul_f32_e32 v44, v215, v215
	v_pk_add_f32 v[36:37], v[46:47], v[36:37]
	v_pk_add_f32 v[34:35], v[34:35], v[40:41]
	v_mul_f32_e32 v1, v216, v216
	v_mul_f32_e32 v48, v218, v218
	v_mul_f32_e32 v49, v219, v219
	v_pk_fma_f32 v[38:39], v[212:213], v[212:213], v[42:43] op_sel_hi:[1,1,0]
	v_pk_fma_f32 v[42:43], v[214:215], v[214:215], v[44:45] op_sel_hi:[1,1,0]
	v_pk_add_f32 v[36:37], v[36:37], v[36:37] op_sel:[0,1] op_sel_hi:[1,0]
	v_pk_add_f32 v[34:35], v[34:35], v[34:35] op_sel:[0,1] op_sel_hi:[1,0]
	v_mov_b32_e32 v39, v48
	v_mov_b32_e32 v43, v49
	v_mov_b32_e32 v37, v1
	v_mov_b32_e32 v35, v45
	v_pk_add_f32 v[38:39], v[38:39], v[42:43]
	v_pk_add_f32 v[34:35], v[36:37], v[34:35]
	s_nop 0
	v_pk_add_f32 v[34:35], v[34:35], v[38:39]
	s_nop 0
	v_add_f32_e32 v1, v34, v35
	v_mov_b32_e32 v239, v1
	ds_bpermute_b32 v240, v8, v236
	ds_bpermute_b32 v241, v8, v237
	ds_bpermute_b32 v242, v8, v238
	ds_bpermute_b32 v243, v8, v239
	s_waitcnt lgkmcnt(3)
	v_add_f32_e32 v236, v236, v240
	s_waitcnt lgkmcnt(2)
	v_add_f32_e32 v237, v237, v241
	s_waitcnt lgkmcnt(1)
	v_add_f32_e32 v238, v238, v242
	s_waitcnt lgkmcnt(0)
	v_add_f32_e32 v239, v239, v243
	ds_bpermute_b32 v240, v9, v236
	ds_bpermute_b32 v241, v9, v237
	ds_bpermute_b32 v242, v9, v238
	ds_bpermute_b32 v243, v9, v239
	s_waitcnt lgkmcnt(3)
	v_add_f32_e32 v236, v236, v240
	s_waitcnt lgkmcnt(2)
	v_add_f32_e32 v237, v237, v241
	s_waitcnt lgkmcnt(1)
	v_add_f32_e32 v238, v238, v242
	s_waitcnt lgkmcnt(0)
	v_add_f32_e32 v239, v239, v243
	ds_bpermute_b32 v240, v10, v236
	ds_bpermute_b32 v241, v10, v237
	ds_bpermute_b32 v242, v10, v238
	ds_bpermute_b32 v243, v10, v239
	s_waitcnt lgkmcnt(3)
	v_add_f32_e32 v236, v236, v240
	s_waitcnt lgkmcnt(2)
	v_add_f32_e32 v237, v237, v241
	s_waitcnt lgkmcnt(1)
	v_add_f32_e32 v238, v238, v242
	s_waitcnt lgkmcnt(0)
	v_add_f32_e32 v239, v239, v243
	ds_bpermute_b32 v240, v11, v236
	ds_bpermute_b32 v241, v11, v237
	ds_bpermute_b32 v242, v11, v238
	ds_bpermute_b32 v243, v11, v239
	s_waitcnt lgkmcnt(3)
	v_add_f32_e32 v236, v236, v240
	s_waitcnt lgkmcnt(2)
	v_add_f32_e32 v237, v237, v241
	s_waitcnt lgkmcnt(1)
	v_add_f32_e32 v238, v238, v242
	s_waitcnt lgkmcnt(0)
	v_add_f32_e32 v239, v239, v243
	ds_bpermute_b32 v240, v12, v236
	ds_bpermute_b32 v241, v12, v237
	ds_bpermute_b32 v242, v12, v238
	ds_bpermute_b32 v243, v12, v239
	s_waitcnt lgkmcnt(3)
	v_add_f32_e32 v236, v236, v240
	s_waitcnt lgkmcnt(2)
	v_add_f32_e32 v237, v237, v241
	s_waitcnt lgkmcnt(1)
	v_add_f32_e32 v238, v238, v242
	s_waitcnt lgkmcnt(0)
	v_add_f32_e32 v239, v239, v243
	ds_bpermute_b32 v240, v13, v236
	ds_bpermute_b32 v241, v13, v237
	ds_bpermute_b32 v242, v13, v238
	ds_bpermute_b32 v243, v13, v239
	s_waitcnt lgkmcnt(3)
	v_add_f32_e32 v236, v236, v240
	s_waitcnt lgkmcnt(2)
	v_add_f32_e32 v237, v237, v241
	s_waitcnt lgkmcnt(1)
	v_add_f32_e32 v238, v238, v242
	s_waitcnt lgkmcnt(0)
	v_add_f32_e32 v239, v239, v243
	v_mov_b32_e32 v1, v236
	v_fmamk_f32 v1, v1, 0x3a800000, v154
	v_mul_f32_e32 v34, 0x4b800000, v1
	v_cmp_gt_f32_e32 vcc, s22, v1
	s_nop 1
	v_cndmask_b32_e32 v1, v1, v34, vcc
	v_rsq_f32_e32 v1, v1
	s_nop 0
	v_mul_f32_e32 v34, 0x45800000, v1
	v_cndmask_b32_e32 v34, v1, v34, vcc
	v_pk_mul_f32 v[130:131], v[130:131], v[34:35] op_sel_hi:[1,0]
	v_pk_mul_f32 v[132:133], v[132:133], v[34:35] op_sel_hi:[1,0]
	v_pk_mul_f32 v[130:131], v[220:221], v[130:131]
	v_pk_mul_f32 v[132:133], v[222:223], v[132:133]
	v_cvt_pk_bf16_f32 v130, v130, v131
	v_cvt_pk_bf16_f32 v131, v132, v133
	v_pk_mul_f32 v[134:135], v[134:135], v[34:35] op_sel_hi:[1,0]
	v_pk_mul_f32 v[136:137], v[136:137], v[34:35] op_sel_hi:[1,0]
	v_pk_mul_f32 v[134:135], v[224:225], v[134:135]
	v_pk_mul_f32 v[136:137], v[226:227], v[136:137]
	v_cvt_pk_bf16_f32 v134, v134, v135
	v_cvt_pk_bf16_f32 v135, v136, v137
	v_pk_mul_f32 v[138:139], v[138:139], v[34:35] op_sel_hi:[1,0]
	v_pk_mul_f32 v[140:141], v[140:141], v[34:35] op_sel_hi:[1,0]
	v_pk_mul_f32 v[138:139], v[228:229], v[138:139]
	v_pk_mul_f32 v[140:141], v[230:231], v[140:141]
	v_cvt_pk_bf16_f32 v138, v138, v139
	v_cvt_pk_bf16_f32 v139, v140, v141
	v_pk_mul_f32 v[142:143], v[142:143], v[34:35] op_sel_hi:[1,0]
	v_pk_mul_f32 v[144:145], v[144:145], v[34:35] op_sel_hi:[1,0]
	v_pk_mul_f32 v[142:143], v[232:233], v[142:143]
	v_pk_mul_f32 v[144:145], v[234:235], v[144:145]
	v_cvt_pk_bf16_f32 v142, v142, v143
	v_cvt_pk_bf16_f32 v143, v144, v145
	global_store_dwordx2 v[4:5], v[130:131], off offset:-1024
	global_store_dwordx2 v[4:5], v[134:135], off offset:-512
	global_store_dwordx2 v[4:5], v[138:139], off
	global_store_dwordx2 v[4:5], v[142:143], off offset:512
	v_lshl_add_u64 v[4:5], v[4:5], 0, s[20:21]
	v_add_u32_e32 v0, s76, v0
	v_mov_b32_e32 v1, v237
	v_fmamk_f32 v1, v1, 0x3a800000, v154
	v_mul_f32_e32 v34, 0x4b800000, v1
	v_cmp_gt_f32_e32 vcc, s22, v1
	s_nop 1
; DI unsigned pk2(float a, float b) { f32x2 v = {a, b}; bf2_t r = __builtin_convertvector(v, bf2_t); return __builtin_bit_cast(unsigned, r); }
; DI void rms_row(const float* x, const float* gain, bf16_t* o, int lane) {
;     ...
;     const float rstd = rsqrtf(wave_sum(s) * (1.f / 1024.f) + 1e-6f);
;     u32x2* op = (u32x2*)o + lane;
; #pragma unroll
;     for (int j = 0; j < 4; ++j) { const f32x4 g = gr[64 * j]; u32x2 w; w.x = pk2(v[j].x * rstd * g.x, v[j].y * rstd * g.y); w.y = pk2(v[j].z * rstd * g.z, v[j].w * rstd * g.w); op[64 * j] = w; }
; DI void phase_conv(const Args& a, int l, LAS unsigned char* lds) {
;     ...
;         for (int m = gw; m < M_TOK; m += NGW) rms_row(a.in[I_X] + (size_t)m * DM, a.in[I_MIXNORM], U + (size_t)m * DM, lane);
	v_cndmask_b32_e32 v1, v1, v34, vcc
	v_rsq_f32_e32 v1, v1
	s_nop 0
	v_mul_f32_e32 v34, 0x45800000, v1
	v_cndmask_b32_e32 v34, v1, v34, vcc
	v_pk_mul_f32 v[146:147], v[146:147], v[34:35] op_sel_hi:[1,0]
	v_pk_mul_f32 v[148:149], v[148:149], v[34:35] op_sel_hi:[1,0]
	v_pk_mul_f32 v[146:147], v[220:221], v[146:147]
	v_pk_mul_f32 v[148:149], v[222:223], v[148:149]
	v_cvt_pk_bf16_f32 v146, v146, v147
	v_cvt_pk_bf16_f32 v147, v148, v149
	v_pk_mul_f32 v[150:151], v[150:151], v[34:35] op_sel_hi:[1,0]
	v_pk_mul_f32 v[152:153], v[152:153], v[34:35] op_sel_hi:[1,0]
	v_pk_mul_f32 v[150:151], v[224:225], v[150:151]
	v_pk_mul_f32 v[152:153], v[226:227], v[152:153]
	v_cvt_pk_bf16_f32 v150, v150, v151
	v_cvt_pk_bf16_f32 v151, v152, v153
	v_pk_mul_f32 v[168:169], v[168:169], v[34:35] op_sel_hi:[1,0]
	v_pk_mul_f32 v[170:171], v[170:171], v[34:35] op_sel_hi:[1,0]
	v_pk_mul_f32 v[168:169], v[228:229], v[168:169]
	v_pk_mul_f32 v[170:171], v[230:231], v[170:171]
	v_cvt_pk_bf16_f32 v168, v168, v169
	v_cvt_pk_bf16_f32 v169, v170, v171
	v_pk_mul_f32 v[172:173], v[172:173], v[34:35] op_sel_hi:[1,0]
	v_pk_mul_f32 v[174:175], v[174:175], v[34:35] op_sel_hi:[1,0]
	v_pk_mul_f32 v[172:173], v[232:233], v[172:173]
	v_pk_mul_f32 v[174:175], v[234:235], v[174:175]
	v_cvt_pk_bf16_f32 v172, v172, v173
	v_cvt_pk_bf16_f32 v173, v174, v175
	global_store_dwordx2 v[4:5], v[146:147], off offset:-1024
	global_store_dwordx2 v[4:5], v[150:151], off offset:-512
	global_store_dwordx2 v[4:5], v[168:169], off
	global_store_dwordx2 v[4:5], v[172:173], off offset:512
	v_lshl_add_u64 v[4:5], v[4:5], 0, s[20:21]
	v_add_u32_e32 v0, s76, v0
	v_mov_b32_e32 v1, v238
	v_fmamk_f32 v1, v1, 0x3a800000, v154
	v_mul_f32_e32 v34, 0x4b800000, v1
	v_cmp_gt_f32_e32 vcc, s22, v1
	s_nop 1
	v_cndmask_b32_e32 v1, v1, v34, vcc
	v_rsq_f32_e32 v1, v1
	s_nop 0
	v_mul_f32_e32 v34, 0x45800000, v1
	v_cndmask_b32_e32 v34, v1, v34, vcc
	v_pk_mul_f32 v[176:177], v[176:177], v[34:35] op_sel_hi:[1,0]
	v_pk_mul_f32 v[178:179], v[178:179], v[34:35] op_sel_hi:[1,0]
	v_pk_mul_f32 v[176:177], v[220:221], v[176:177]
	v_pk_mul_f32 v[178:179], v[222:223], v[178:179]
	v_cvt_pk_bf16_f32 v176, v176, v177
	v_cvt_pk_bf16_f32 v177, v178, v179
	v_pk_mul_f32 v[180:181], v[180:181], v[34:35] op_sel_hi:[1,0]
	v_pk_mul_f32 v[182:183], v[182:183], v[34:35] op_sel_hi:[1,0]
	v_pk_mul_f32 v[180:181], v[224:225], v[180:181]
	v_pk_mul_f32 v[182:183], v[226:227], v[182:183]
	v_cvt_pk_bf16_f32 v180, v180, v181
	v_cvt_pk_bf16_f32 v181, v182, v183
	v_pk_mul_f32 v[184:185], v[184:185], v[34:35] op_sel_hi:[1,0]
	v_pk_mul_f32 v[186:187], v[186:187], v[34:35] op_sel_hi:[1,0]
	v_pk_mul_f32 v[184:185], v[228:229], v[184:185]
	v_pk_mul_f32 v[186:187], v[230:231], v[186:187]
	v_cvt_pk_bf16_f32 v184, v184, v185
	v_cvt_pk_bf16_f32 v185, v186, v187
	v_pk_mul_f32 v[196:197], v[196:197], v[34:35] op_sel_hi:[1,0]
	v_pk_mul_f32 v[198:199], v[198:199], v[34:35] op_sel_hi:[1,0]
	v_pk_mul_f32 v[196:197], v[232:233], v[196:197]
	v_pk_mul_f32 v[198:199], v[234:235], v[198:199]
	v_cvt_pk_bf16_f32 v196, v196, v197
	v_cvt_pk_bf16_f32 v197, v198, v199
	global_store_dwordx2 v[4:5], v[176:177], off offset:-1024
	global_store_dwordx2 v[4:5], v[180:181], off offset:-512
	global_store_dwordx2 v[4:5], v[184:185], off
	global_store_dwordx2 v[4:5], v[196:197], off offset:512
	v_lshl_add_u64 v[4:5], v[4:5], 0, s[20:21]
	v_add_u32_e32 v0, s76, v0
	v_mov_b32_e32 v1, v239
	v_fmamk_f32 v1, v1, 0x3a800000, v154
	v_mul_f32_e32 v34, 0x4b800000, v1
	v_cmp_gt_f32_e32 vcc, s22, v1
	s_nop 1
	v_cndmask_b32_e32 v1, v1, v34, vcc
	v_rsq_f32_e32 v1, v1
	s_nop 0
	v_mul_f32_e32 v34, 0x45800000, v1
	v_cndmask_b32_e32 v34, v1, v34, vcc
	v_pk_mul_f32 v[200:201], v[200:201], v[34:35] op_sel_hi:[1,0]
	v_pk_mul_f32 v[202:203], v[202:203], v[34:35] op_sel_hi:[1,0]
	v_pk_mul_f32 v[200:201], v[220:221], v[200:201]
	v_pk_mul_f32 v[202:203], v[222:223], v[202:203]
	v_cvt_pk_bf16_f32 v200, v200, v201
	v_cvt_pk_bf16_f32 v201, v202, v203
	v_pk_mul_f32 v[204:205], v[204:205], v[34:35] op_sel_hi:[1,0]
	v_pk_mul_f32 v[206:207], v[206:207], v[34:35] op_sel_hi:[1,0]
	v_pk_mul_f32 v[204:205], v[224:225], v[204:205]
	v_pk_mul_f32 v[206:207], v[226:227], v[206:207]
	v_cvt_pk_bf16_f32 v204, v204, v205
	v_cvt_pk_bf16_f32 v205, v206, v207
	v_pk_mul_f32 v[212:213], v[212:213], v[34:35] op_sel_hi:[1,0]
	v_pk_mul_f32 v[214:215], v[214:215], v[34:35] op_sel_hi:[1,0]
	v_pk_mul_f32 v[212:213], v[228:229], v[212:213]
	v_pk_mul_f32 v[214:215], v[230:231], v[214:215]
	v_cvt_pk_bf16_f32 v212, v212, v213
	v_cvt_pk_bf16_f32 v213, v214, v215
	v_pk_mul_f32 v[216:217], v[216:217], v[34:35] op_sel_hi:[1,0]
	v_pk_mul_f32 v[218:219], v[218:219], v[34:35] op_sel_hi:[1,0]
	v_pk_mul_f32 v[216:217], v[232:233], v[216:217]
	v_pk_mul_f32 v[218:219], v[234:235], v[218:219]
	v_cvt_pk_bf16_f32 v216, v216, v217
	v_cvt_pk_bf16_f32 v217, v218, v219
	global_store_dwordx2 v[4:5], v[200:201], off offset:-1024
	global_store_dwordx2 v[4:5], v[204:205], off offset:-512
	global_store_dwordx2 v[4:5], v[212:213], off
	global_store_dwordx2 v[4:5], v[216:217], off offset:512
	v_lshl_add_u64 v[4:5], v[4:5], 0, s[20:21]
	v_add_u32_e32 v0, s76, v0
	s_movk_i32 s4, 0x7fff
	v_cmp_lt_i32_e32 vcc, s4, v0
	s_cbranch_vccnz .LBB0_1602
